# GEMM K-loops: second barrier moved from after MFMA 1 to after MFMA 10 (stage k+2 DMAs before it, wait vmcnt(6)), only the stage k+3 DMA chain stays behind it
# speedup vs baseline: 1.0056x; 1.0000x over previous
.LBB0_134:
	s_mul_i32 s17, s16, 0x6000
	v_add_u32_e32 v146, s17, v145
	v_add_u32_e32 v147, s17, v143
	v_add_u32_e32 v198, v146, v141
	v_add_u32_e32 v199, v147, v141
	v_add_u32_e32 v200, v146, v142
	v_add_u32_e32 v201, v147, v142
	s_waitcnt vmcnt(6)
	s_barrier
	ds_read_b128 v[146:149], v198
	ds_read_b128 v[150:153], v198 offset:2048
	ds_read_b128 v[154:157], v199
	ds_read_b128 v[158:161], v199 offset:2048
	ds_read_b128 v[162:165], v199 offset:4096
	ds_read_b128 v[170:173], v199 offset:6144
	ds_read_b128 v[174:177], v200
	ds_read_b128 v[178:181], v200 offset:2048
	ds_read_b128 v[182:185], v201
	ds_read_b128 v[186:189], v201 offset:2048
	ds_read_b128 v[190:193], v201 offset:4096
	ds_read_b128 v[194:197], v201 offset:6144
	s_waitcnt lgkmcnt(0)
	v_mfma_f32_32x32x16_bf16 v[114:129], v[146:149], v[154:157], v[114:129]
	v_mfma_f32_32x32x16_bf16 v[82:97], v[146:149], v[158:161], v[82:97]
	v_mfma_f32_32x32x16_bf16 v[50:65], v[146:149], v[162:165], v[50:65]
	v_mfma_f32_32x32x16_bf16 v[18:33], v[146:149], v[170:173], v[18:33]
	s_add_i32 s18, s17, 0xffffa000
	s_cmp_gt_i32 s16, 0
	s_cselect_b32 s18, s18, 0xc000
	v_add_u32_e32 v148, s18, v139
	v_lshl_add_u64 v[136:137], v[132:133], 0, v[0:1]
	v_readfirstlane_b32 s18, v148
	v_add_u32_e32 v146, 0x1000, v148
	v_lshl_add_u64 v[134:135], v[136:137], 0, s[24:25]
	s_mov_b32 m0, s18
	v_readfirstlane_b32 s18, v146
	v_add_u32_e32 v146, 0x2000, v148
	global_load_lds_dwordx4 v[134:135], off
	v_mfma_f32_32x32x16_bf16 v[98:113], v[150:153], v[154:157], v[98:113]
	v_lshl_add_u64 v[134:135], v[136:137], 0, s[36:37]
	s_mov_b32 m0, s18
	v_readfirstlane_b32 s18, v146
	v_add_u32_e32 v146, 0x3000, v148
	global_load_lds_dwordx4 v[134:135], off
	v_mfma_f32_32x32x16_bf16 v[66:81], v[150:153], v[158:161], v[66:81]
	v_lshl_add_u64 v[134:135], v[136:137], 0, s[38:39]
	s_mov_b32 m0, s18
	v_readfirstlane_b32 s18, v146
	global_load_lds_dwordx4 v[134:135], off
	v_mfma_f32_32x32x16_bf16 v[34:49], v[150:153], v[162:165], v[34:49]
	v_lshl_add_u64 v[134:135], v[136:137], 0, s[40:41]
	s_mov_b32 m0, s18
	v_add_u32_e32 v149, 0x4000, v148
	global_load_lds_dwordx4 v[134:135], off
	v_mfma_f32_32x32x16_bf16 v[2:17], v[150:153], v[170:173], v[2:17]
	v_lshl_add_u64 v[134:135], v[130:131], 0, v[0:1]
	v_readfirstlane_b32 s18, v149
	v_lshl_add_u64 v[146:147], v[134:135], 0, s[44:45]
	s_mov_b32 m0, s18
	s_mov_b64 s[18:19], 0x71000
	v_add_u32_e32 v148, 0x5000, v148
	global_load_lds_dwordx4 v[146:147], off
	v_mfma_f32_32x32x16_bf16 v[114:129], v[174:177], v[182:185], v[114:129]
	v_lshl_add_u64 v[146:147], v[134:135], 0, s[18:19]
	v_readfirstlane_b32 s18, v148
	s_mov_b32 m0, s18
	v_lshl_add_u64 v[130:131], v[130:131], 0, s[44:45]
	global_load_lds_dwordx4 v[146:147], off
	v_mfma_f32_32x32x16_bf16 v[98:113], v[178:181], v[182:185], v[98:113]
	s_waitcnt vmcnt(6)
	s_barrier
	s_add_i32 s17, s16, 1
	s_cmp_lg_u32 s16, 2
	s_cselect_b32 s16, s17, 0
	s_mul_i32 s17, s16, 0x6000
	s_add_i32 s18, s17, 0xffffa000
	s_cmp_gt_i32 s16, 0
	s_cselect_b32 s18, s18, 0xc000
	v_lshl_add_u64 v[132:133], v[132:133], 0, s[96:97]
	v_add_u32_e32 v148, s18, v139
	v_add_u32_e32 v149, 0x1000, v148
	v_readfirstlane_b32 s18, v148
	v_lshl_add_u64 v[146:147], v[136:137], 0, s[88:89]
	s_mov_b32 m0, s18
	v_readfirstlane_b32 s18, v149
	v_add_u32_e32 v149, 0x2000, v148
	global_load_lds_dwordx4 v[146:147], off
	v_mfma_f32_32x32x16_bf16 v[82:97], v[174:177], v[186:189], v[82:97]
	v_lshl_add_u64 v[146:147], v[136:137], 0, s[4:5]
	s_mov_b32 m0, s18
	v_readfirstlane_b32 s18, v149
	global_load_lds_dwordx4 v[146:147], off
	v_mfma_f32_32x32x16_bf16 v[66:81], v[178:181], v[186:189], v[66:81]
	v_lshl_add_u64 v[146:147], v[136:137], 0, s[84:85]
	s_mov_b32 m0, s18
	v_lshl_add_u64 v[136:137], v[136:137], 0, s[86:87]
	global_load_lds_dwordx4 v[146:147], off
	v_mfma_f32_32x32x16_bf16 v[50:65], v[174:177], v[190:193], v[50:65]
	v_add_u32_e32 v146, 0x3000, v148
	s_nop 0
	v_readfirstlane_b32 s18, v146
	s_mov_b32 m0, s18
	s_mov_b64 s[18:19], 0xa8000
	v_add_u32_e32 v146, 0x4000, v148
	global_load_lds_dwordx4 v[136:137], off
	v_mfma_f32_32x32x16_bf16 v[34:49], v[178:181], v[190:193], v[34:49]
	v_lshl_add_u64 v[136:137], v[134:135], 0, s[18:19]
	v_readfirstlane_b32 s18, v146
	s_mov_b32 m0, s18
	s_mov_b64 s[18:19], 0xa9000
	global_load_lds_dwordx4 v[136:137], off
	v_mfma_f32_32x32x16_bf16 v[18:33], v[174:177], v[194:197], v[18:33]
	v_add_u32_e32 v136, 0x5000, v148
	v_lshl_add_u64 v[134:135], v[134:135], 0, s[18:19]
	v_readfirstlane_b32 s18, v136
	s_mov_b32 m0, s18
	s_nop 0
	global_load_lds_dwordx4 v[134:135], off
	v_mfma_f32_32x32x16_bf16 v[2:17], v[178:181], v[194:197], v[2:17]
	v_add_u32_e32 v134, s17, v145
	v_add_u32_e32 v135, s17, v143
	s_add_i32 s17, s16, 1
	s_cmp_lg_u32 s16, 2
	s_cselect_b32 s16, s17, 0
	s_add_i32 s15, s15, -2
	s_cmp_eq_u32 s15, 0
	v_add_u32_e32 v194, v134, v141
	v_add_u32_e32 v195, v135, v141
	v_add_u32_e32 v196, v134, v142
	v_add_u32_e32 v197, v135, v142
	ds_read_b128 v[134:137], v194
	ds_read_b128 v[146:149], v194 offset:2048
	ds_read_b128 v[150:153], v195
	ds_read_b128 v[154:157], v195 offset:2048
	ds_read_b128 v[158:161], v195 offset:4096
	ds_read_b128 v[162:165], v195 offset:6144
	ds_read_b128 v[170:173], v196
	ds_read_b128 v[174:177], v196 offset:2048
	ds_read_b128 v[178:181], v197
	ds_read_b128 v[182:185], v197 offset:2048
	ds_read_b128 v[186:189], v197 offset:4096
	ds_read_b128 v[190:193], v197 offset:6144
	s_waitcnt lgkmcnt(0)
	s_nop 0
	v_mfma_f32_32x32x16_bf16 v[114:129], v[134:137], v[150:153], v[114:129]
	v_mfma_f32_32x32x16_bf16 v[98:113], v[146:149], v[150:153], v[98:113]
	v_mfma_f32_32x32x16_bf16 v[82:97], v[134:137], v[154:157], v[82:97]
	v_mfma_f32_32x32x16_bf16 v[66:81], v[146:149], v[154:157], v[66:81]
	v_mfma_f32_32x32x16_bf16 v[50:65], v[134:137], v[158:161], v[50:65]
	v_mfma_f32_32x32x16_bf16 v[34:49], v[146:149], v[158:161], v[34:49]
	v_mfma_f32_32x32x16_bf16 v[18:33], v[134:137], v[162:165], v[18:33]
	v_mfma_f32_32x32x16_bf16 v[2:17], v[146:149], v[162:165], v[2:17]
	v_mfma_f32_32x32x16_bf16 v[114:129], v[170:173], v[178:181], v[114:129]
	v_mfma_f32_32x32x16_bf16 v[98:113], v[174:177], v[178:181], v[98:113]
	v_mfma_f32_32x32x16_bf16 v[82:97], v[170:173], v[182:185], v[82:97]
	v_mfma_f32_32x32x16_bf16 v[66:81], v[174:177], v[182:185], v[66:81]
	v_mfma_f32_32x32x16_bf16 v[50:65], v[170:173], v[186:189], v[50:65]
	v_mfma_f32_32x32x16_bf16 v[34:49], v[174:177], v[186:189], v[34:49]
	v_mfma_f32_32x32x16_bf16 v[18:33], v[170:173], v[190:193], v[18:33]
	v_mfma_f32_32x32x16_bf16 v[2:17], v[174:177], v[190:193], v[2:17]
	s_cbranch_scc0 .LBB0_134
	s_waitcnt vmcnt(6)
	s_barrier
	v_add_u32_e32 v0, v145, v141
	v_add_u32_e32 v190, v143, v141
	v_add_u32_e32 v145, v145, v142
	v_add_u32_e32 v191, v143, v142
	ds_read_b128 v[130:133], v0
	ds_read_b128 v[134:137], v0 offset:2048
	ds_read_b128 v[146:149], v190
	ds_read_b128 v[150:153], v190 offset:2048
	ds_read_b128 v[154:157], v190 offset:4096
	ds_read_b128 v[158:161], v190 offset:6144
	ds_read_b128 v[162:165], v145
	ds_read_b128 v[170:173], v145 offset:2048
	ds_read_b128 v[174:177], v191
	ds_read_b128 v[178:181], v191 offset:2048
	ds_read_b128 v[182:185], v191 offset:4096
	ds_read_b128 v[186:189], v191 offset:6144
	s_waitcnt lgkmcnt(0)
	v_or_b32_e32 v0, 0xa000, v144
	v_mfma_f32_32x32x16_bf16 v[50:65], v[130:133], v[154:157], v[50:65]
	s_waitcnt vmcnt(0)
	s_barrier
	s_lshl_b32 s15, s14, 1
	v_mfma_f32_32x32x16_bf16 v[34:49], v[134:137], v[154:157], v[34:49]
	v_mfma_f32_32x32x16_bf16 v[82:97], v[130:133], v[150:153], v[82:97]
	v_mfma_f32_32x32x16_bf16 v[66:81], v[134:137], v[150:153], v[66:81]
	v_mfma_f32_32x32x16_bf16 v[2:17], v[134:137], v[158:161], v[2:17]
	v_mfma_f32_32x32x16_bf16 v[114:129], v[130:133], v[146:149], v[114:129]
	v_mfma_f32_32x32x16_bf16 v[98:113], v[134:137], v[146:149], v[98:113]
	v_mfma_f32_32x32x16_bf16 v[18:33], v[130:133], v[158:161], v[18:33]
	v_add_u32_e32 v130, 0x6000, v143
	v_mfma_f32_32x32x16_bf16 v[50:65], v[162:165], v[182:185], v[50:65]
	v_mfma_f32_32x32x16_bf16 v[34:49], v[170:173], v[182:185], v[34:49]
	v_mfma_f32_32x32x16_bf16 v[82:97], v[162:165], v[178:181], v[82:97]
	v_mfma_f32_32x32x16_bf16 v[66:81], v[170:173], v[178:181], v[66:81]
	v_mfma_f32_32x32x16_bf16 v[2:17], v[170:173], v[186:189], v[2:17]
	v_mfma_f32_32x32x16_bf16 v[114:129], v[162:165], v[174:177], v[114:129]
	v_mfma_f32_32x32x16_bf16 v[98:113], v[170:173], v[174:177], v[98:113]
	v_mfma_f32_32x32x16_bf16 v[18:33], v[162:165], v[186:189], v[18:33]
	v_add_u32_e32 v186, v141, v0
	v_add_u32_e32 v141, v141, v130
	v_add_u32_e32 v0, v142, v0
	v_add_u32_e32 v187, v142, v130
	ds_read_b128 v[130:133], v186
	ds_read_b128 v[134:137], v186 offset:2048
	ds_read_b128 v[142:145], v141
	ds_read_b128 v[146:149], v141 offset:2048
	ds_read_b128 v[150:153], v141 offset:4096
	ds_read_b128 v[154:157], v141 offset:6144
	ds_read_b128 v[158:161], v0
	ds_read_b128 v[162:165], v0 offset:2048
	ds_read_b128 v[170:173], v187
	ds_read_b128 v[174:177], v187 offset:2048
	ds_read_b128 v[178:181], v187 offset:4096
	ds_read_b128 v[182:185], v187 offset:6144
	s_waitcnt lgkmcnt(0)
	v_lshlrev_b32_e32 v0, 1, v138
	v_and_b32_e32 v0, 0x80, v0
	v_mfma_f32_32x32x16_bf16 v[50:65], v[130:133], v[150:153], v[50:65]
	v_and_b32_e32 v141, 0xfffff9f, v138
	v_lshl_or_b32 v0, v140, 3, v0
	v_mad_u64_u32 v[140:141], s[16:17], v141, s3, v[0:1]
	s_waitcnt vmcnt(0) lgkmcnt(0)
	s_barrier
	v_mfma_f32_32x32x16_bf16 v[34:49], v[134:137], v[150:153], v[34:49]
	v_mfma_f32_32x32x16_bf16 v[82:97], v[130:133], v[146:149], v[82:97]
	v_mfma_f32_32x32x16_bf16 v[66:81], v[134:137], v[146:149], v[66:81]
	v_mfma_f32_32x32x16_bf16 v[2:17], v[134:137], v[154:157], v[2:17]
	v_mfma_f32_32x32x16_bf16 v[114:129], v[130:133], v[142:145], v[114:129]
	v_mfma_f32_32x32x16_bf16 v[98:113], v[134:137], v[142:145], v[98:113]
	v_mfma_f32_32x32x16_bf16 v[18:33], v[130:133], v[154:157], v[18:33]
	v_mfma_f32_32x32x16_bf16 v[50:65], v[158:161], v[178:181], v[50:65]
	v_mfma_f32_32x32x16_bf16 v[34:49], v[162:165], v[178:181], v[34:49]
	s_nop 10
	v_cvt_pk_bf16_f32 v50, v50, v51
	v_cvt_pk_bf16_f32 v51, v52, v53
	v_cvt_pk_bf16_f32 v52, v54, v55
	v_add_u32_e32 v54, 0x4000, v140
	v_cvt_pk_bf16_f32 v53, v56, v57
	ds_write2_b64 v54, v[50:51], v[52:53] offset0:128 offset1:130
	v_cvt_pk_bf16_f32 v50, v58, v59
	v_mfma_f32_32x32x16_bf16 v[82:97], v[158:161], v[174:177], v[82:97]
	v_cvt_pk_bf16_f32 v34, v34, v35
	v_cvt_pk_bf16_f32 v35, v36, v37
	v_cvt_pk_bf16_f32 v36, v38, v39
	v_cvt_pk_bf16_f32 v37, v40, v41
	ds_write2_b64 v54, v[34:35], v[36:37] offset0:136 offset1:138
	v_cvt_pk_bf16_f32 v34, v42, v43
	v_cvt_pk_bf16_f32 v35, v44, v45
	v_mfma_f32_32x32x16_bf16 v[66:81], v[162:165], v[174:177], v[66:81]
	v_cvt_pk_bf16_f32 v36, v46, v47
	v_cvt_pk_bf16_f32 v37, v48, v49
	ds_write2_b64 v54, v[34:35], v[36:37] offset0:140 offset1:142
	v_or_b32_e32 v34, 0x60, v138
	v_mad_u64_u32 v[34:35], s[16:17], v34, s3, v[0:1]
	v_cvt_pk_bf16_f32 v82, v82, v83
	v_mfma_f32_32x32x16_bf16 v[2:17], v[162:165], v[182:185], v[2:17]
	v_cvt_pk_bf16_f32 v83, v84, v85
	v_cvt_pk_bf16_f32 v84, v86, v87
	v_add_u32_e32 v86, 0x2000, v140
	s_nop 1
	v_cvt_pk_bf16_f32 v66, v66, v67
	v_cvt_pk_bf16_f32 v67, v68, v69
	v_cvt_pk_bf16_f32 v68, v70, v71
	v_cvt_pk_bf16_f32 v69, v72, v73
	v_mfma_f32_32x32x16_bf16 v[114:129], v[158:161], v[170:173], v[114:129]
	s_nop 1
	v_cvt_pk_bf16_f32 v2, v2, v3
	v_cvt_pk_bf16_f32 v3, v4, v5
	v_cvt_pk_bf16_f32 v4, v6, v7
	v_cvt_pk_bf16_f32 v5, v8, v9
	s_add_u32 s16, s92, s15
	v_cvt_pk_bf16_f32 v85, v88, v89
	ds_write2_b64 v86, v[66:67], v[68:69] offset0:72 offset1:74
	v_mfma_f32_32x32x16_bf16 v[98:113], v[162:165], v[170:173], v[98:113]
	s_nop 1
	v_cvt_pk_bf16_f32 v114, v114, v115
	v_cvt_pk_bf16_f32 v115, v116, v117
	v_cvt_pk_bf16_f32 v116, v118, v119
	v_cvt_pk_bf16_f32 v117, v120, v121
	v_cvt_pk_bf16_f32 v66, v74, v75
	v_cvt_pk_bf16_f32 v67, v76, v77
	v_cvt_pk_bf16_f32 v68, v78, v79
	v_mfma_f32_32x32x16_bf16 v[18:33], v[158:161], v[182:185], v[18:33]
	s_nop 1
	v_cvt_pk_bf16_f32 v98, v98, v99
	v_cvt_pk_bf16_f32 v99, v100, v101
	v_cvt_pk_bf16_f32 v100, v102, v103
	v_cvt_pk_bf16_f32 v101, v104, v105
	v_cvt_pk_bf16_f32 v69, v80, v81
	ds_write2_b64 v34, v[2:3], v[4:5] offset0:8 offset1:10
	v_cvt_pk_bf16_f32 v2, v10, v11
	s_nop 2
	v_cvt_pk_bf16_f32 v18, v18, v19
	v_cvt_pk_bf16_f32 v19, v20, v21
	v_cvt_pk_bf16_f32 v20, v22, v23
	v_cvt_pk_bf16_f32 v21, v24, v25
	v_cvt_pk_bf16_f32 v3, v12, v13
	v_cvt_pk_bf16_f32 v4, v14, v15
	v_cvt_pk_bf16_f32 v5, v16, v17
	v_and_b32_e32 v0, 0xf0, v139
	s_addc_u32 s17, s93, 0
	ds_write2_b64 v140, v[114:115], v[116:117] offset1:2
	v_cvt_pk_bf16_f32 v114, v122, v123
	v_cvt_pk_bf16_f32 v115, v124, v125
	v_cvt_pk_bf16_f32 v116, v126, v127
	v_cvt_pk_bf16_f32 v117, v128, v129
	ds_write2_b64 v140, v[98:99], v[100:101] offset0:8 offset1:10
	v_cvt_pk_bf16_f32 v98, v106, v107
	v_cvt_pk_bf16_f32 v99, v108, v109
	v_cvt_pk_bf16_f32 v100, v110, v111
	v_cvt_pk_bf16_f32 v101, v112, v113
	ds_write2_b64 v86, v[82:83], v[84:85] offset0:64 offset1:66
	v_cvt_pk_bf16_f32 v82, v90, v91
	v_cvt_pk_bf16_f32 v83, v92, v93
	v_cvt_pk_bf16_f32 v84, v94, v95
	v_cvt_pk_bf16_f32 v85, v96, v97
	ds_write2_b64 v86, v[66:67], v[68:69] offset0:76 offset1:78
	v_cvt_pk_bf16_f32 v51, v60, v61
	v_cvt_pk_bf16_f32 v52, v62, v63
	v_cvt_pk_bf16_f32 v53, v64, v65
	ds_write2_b64 v34, v[18:19], v[20:21] offset1:2
	v_cvt_pk_bf16_f32 v18, v26, v27
	v_cvt_pk_bf16_f32 v19, v28, v29
	v_cvt_pk_bf16_f32 v20, v30, v31
	v_cvt_pk_bf16_f32 v21, v32, v33
	ds_write2_b64 v34, v[2:3], v[4:5] offset0:12 offset1:14
	v_lshl_add_u64 v[2:3], s[16:17], 0, v[0:1]
	s_mov_b32 s15, 0
	ds_write2_b64 v140, v[114:115], v[116:117] offset0:4 offset1:6
	ds_write2_b64 v140, v[98:99], v[100:101] offset0:12 offset1:14
	ds_write2_b64 v86, v[82:83], v[84:85] offset0:68 offset1:70
	ds_write2_b64 v54, v[50:51], v[52:53] offset0:132 offset1:134
	ds_write2_b64 v34, v[18:19], v[20:21] offset0:4 offset1:6
	s_waitcnt lgkmcnt(0)
	s_barrier

.LBB0_1322:
	s_mul_i32 s16, s13, 0x6000
	v_add_u32_e32 v146, s16, v144
	v_add_u32_e32 v147, s16, v142
	v_add_u32_e32 v198, v146, v131
	v_add_u32_e32 v199, v147, v131
	v_add_u32_e32 v200, v146, v141
	v_add_u32_e32 v201, v147, v141
	s_waitcnt vmcnt(6)
	s_barrier
	ds_read_b128 v[146:149], v198
	ds_read_b128 v[150:153], v198 offset:2048
	ds_read_b128 v[154:157], v199
	ds_read_b128 v[158:161], v199 offset:2048
	ds_read_b128 v[162:165], v199 offset:4096
	ds_read_b128 v[170:173], v199 offset:6144
	ds_read_b128 v[174:177], v200
	ds_read_b128 v[178:181], v200 offset:2048
	ds_read_b128 v[182:185], v201
	ds_read_b128 v[186:189], v201 offset:2048
	ds_read_b128 v[190:193], v201 offset:4096
	ds_read_b128 v[194:197], v201 offset:6144
	s_waitcnt lgkmcnt(0)
	v_mfma_f32_32x32x16_bf16 v[114:129], v[146:149], v[154:157], v[114:129]
	v_mfma_f32_32x32x16_bf16 v[82:97], v[146:149], v[158:161], v[82:97]
	v_mfma_f32_32x32x16_bf16 v[50:65], v[146:149], v[162:165], v[50:65]
	v_mfma_f32_32x32x16_bf16 v[18:33], v[146:149], v[170:173], v[18:33]
	s_add_i32 s14, s16, 0xffffa000
	s_cmp_gt_i32 s13, 0
	s_cselect_b32 s14, s14, 0xc000
	v_add_u32_e32 v148, s14, v145
	v_lshl_add_u64 v[138:139], v[134:135], 0, v[0:1]
	v_readfirstlane_b32 s14, v148
	v_add_u32_e32 v146, 0x1000, v148
	v_lshl_add_u64 v[136:137], v[138:139], 0, s[18:19]
	s_mov_b32 m0, s14
	v_readfirstlane_b32 s14, v146
	v_add_u32_e32 v146, 0x2000, v148
	global_load_lds_dwordx4 v[136:137], off
	v_mfma_f32_32x32x16_bf16 v[98:113], v[150:153], v[154:157], v[98:113]
	v_lshl_add_u64 v[136:137], v[138:139], 0, s[20:21]
	s_mov_b32 m0, s14
	v_readfirstlane_b32 s14, v146
	v_add_u32_e32 v146, 0x3000, v148
	global_load_lds_dwordx4 v[136:137], off
	v_mfma_f32_32x32x16_bf16 v[66:81], v[150:153], v[158:161], v[66:81]
	v_lshl_add_u64 v[136:137], v[138:139], 0, s[40:41]
	s_mov_b32 m0, s14
	v_readfirstlane_b32 s14, v146
	global_load_lds_dwordx4 v[136:137], off
	v_mfma_f32_32x32x16_bf16 v[34:49], v[150:153], v[162:165], v[34:49]
	v_lshl_add_u64 v[136:137], v[138:139], 0, s[42:43]
	s_mov_b32 m0, s14
	s_mov_b64 s[14:15], 0x720000
	global_load_lds_dwordx4 v[136:137], off
	v_mfma_f32_32x32x16_bf16 v[2:17], v[150:153], v[170:173], v[2:17]
	v_lshl_add_u64 v[136:137], v[132:133], 0, v[0:1]
	v_add_u32_e32 v149, 0x4000, v148
	v_lshl_add_u64 v[146:147], v[136:137], 0, s[14:15]
	v_readfirstlane_b32 s14, v149
	s_mov_b32 m0, s14
	s_mov_b64 s[14:15], 0x721000
	v_add_u32_e32 v148, 0x5000, v148
	global_load_lds_dwordx4 v[146:147], off
	v_mfma_f32_32x32x16_bf16 v[114:129], v[174:177], v[182:185], v[114:129]
	v_lshl_add_u64 v[146:147], v[136:137], 0, s[14:15]
	v_readfirstlane_b32 s14, v148
	s_mov_b32 m0, s14
	s_add_i32 s14, s13, 1
	s_cmp_lg_u32 s13, 2
	s_cselect_b32 s13, s14, 0
	s_mul_i32 s14, s13, 0x6000
	s_add_i32 s15, s14, 0xffffa000
	global_load_lds_dwordx4 v[146:147], off
	v_mfma_f32_32x32x16_bf16 v[98:113], v[178:181], v[182:185], v[98:113]
	s_waitcnt vmcnt(6)
	s_barrier
	s_cmp_gt_i32 s13, 0
	s_cselect_b32 s15, s15, 0xc000
	s_mov_b64 s[16:17], 0x730000
	v_lshl_add_u64 v[132:133], v[132:133], 0, s[58:59]
	v_lshl_add_u64 v[134:135], v[134:135], 0, s[96:97]
	v_add_u32_e32 v148, s15, v145
	v_add_u32_e32 v149, 0x1000, v148
	v_readfirstlane_b32 s15, v148
	v_lshl_add_u64 v[146:147], v[138:139], 0, s[46:47]
	s_mov_b32 m0, s15
	v_readfirstlane_b32 s15, v149
	v_add_u32_e32 v149, 0x2000, v148
	global_load_lds_dwordx4 v[146:147], off
	v_mfma_f32_32x32x16_bf16 v[82:97], v[174:177], v[186:189], v[82:97]
	v_lshl_add_u64 v[146:147], v[138:139], 0, s[48:49]
	s_mov_b32 m0, s15
	v_readfirstlane_b32 s15, v149
	global_load_lds_dwordx4 v[146:147], off
	v_mfma_f32_32x32x16_bf16 v[66:81], v[178:181], v[186:189], v[66:81]
	v_lshl_add_u64 v[146:147], v[138:139], 0, s[50:51]
	s_mov_b32 m0, s15
	v_lshl_add_u64 v[138:139], v[138:139], 0, s[56:57]
	global_load_lds_dwordx4 v[146:147], off
	v_mfma_f32_32x32x16_bf16 v[50:65], v[174:177], v[190:193], v[50:65]
	v_add_u32_e32 v146, 0x3000, v148
	s_nop 0
	v_readfirstlane_b32 s15, v146
	v_add_u32_e32 v146, 0x4000, v148
	s_mov_b32 m0, s15
	v_readfirstlane_b32 s15, v146
	global_load_lds_dwordx4 v[138:139], off
	v_mfma_f32_32x32x16_bf16 v[34:49], v[178:181], v[190:193], v[34:49]
	v_lshl_add_u64 v[138:139], v[136:137], 0, s[16:17]
	s_mov_b32 m0, s15
	s_mov_b64 s[16:17], 0x731000
	global_load_lds_dwordx4 v[138:139], off
	v_mfma_f32_32x32x16_bf16 v[18:33], v[174:177], v[194:197], v[18:33]
	v_add_u32_e32 v138, 0x5000, v148
	v_lshl_add_u64 v[136:137], v[136:137], 0, s[16:17]
	v_readfirstlane_b32 s15, v138
	s_mov_b32 m0, s15
	s_nop 0
	global_load_lds_dwordx4 v[136:137], off
	v_mfma_f32_32x32x16_bf16 v[2:17], v[178:181], v[194:197], v[2:17]
	v_add_u32_e32 v136, s14, v144
	v_add_u32_e32 v137, s14, v142
	s_add_i32 s14, s13, 1
	s_cmp_lg_u32 s13, 2
	s_cselect_b32 s13, s14, 0
	s_add_i32 s12, s12, -2
	s_cmp_eq_u32 s12, 0
	v_add_u32_e32 v194, v136, v131
	v_add_u32_e32 v195, v137, v131
	v_add_u32_e32 v196, v136, v141
	v_add_u32_e32 v197, v137, v141
	ds_read_b128 v[136:139], v194
	ds_read_b128 v[146:149], v194 offset:2048
	ds_read_b128 v[150:153], v195
	ds_read_b128 v[154:157], v195 offset:2048
	ds_read_b128 v[158:161], v195 offset:4096
	ds_read_b128 v[162:165], v195 offset:6144
	ds_read_b128 v[170:173], v196
	ds_read_b128 v[174:177], v196 offset:2048
	ds_read_b128 v[178:181], v197
	ds_read_b128 v[182:185], v197 offset:2048
	ds_read_b128 v[186:189], v197 offset:4096
	ds_read_b128 v[190:193], v197 offset:6144
	s_waitcnt lgkmcnt(0)
	s_nop 0
	v_mfma_f32_32x32x16_bf16 v[114:129], v[136:139], v[150:153], v[114:129]
	v_mfma_f32_32x32x16_bf16 v[98:113], v[146:149], v[150:153], v[98:113]
	v_mfma_f32_32x32x16_bf16 v[82:97], v[136:139], v[154:157], v[82:97]
	v_mfma_f32_32x32x16_bf16 v[66:81], v[146:149], v[154:157], v[66:81]
	v_mfma_f32_32x32x16_bf16 v[50:65], v[136:139], v[158:161], v[50:65]
	v_mfma_f32_32x32x16_bf16 v[34:49], v[146:149], v[158:161], v[34:49]
	v_mfma_f32_32x32x16_bf16 v[18:33], v[136:139], v[162:165], v[18:33]
	v_mfma_f32_32x32x16_bf16 v[2:17], v[146:149], v[162:165], v[2:17]
	v_mfma_f32_32x32x16_bf16 v[114:129], v[170:173], v[178:181], v[114:129]
	v_mfma_f32_32x32x16_bf16 v[98:113], v[174:177], v[178:181], v[98:113]
	v_mfma_f32_32x32x16_bf16 v[82:97], v[170:173], v[182:185], v[82:97]
	v_mfma_f32_32x32x16_bf16 v[66:81], v[174:177], v[182:185], v[66:81]
	v_mfma_f32_32x32x16_bf16 v[50:65], v[170:173], v[186:189], v[50:65]
	v_mfma_f32_32x32x16_bf16 v[34:49], v[174:177], v[186:189], v[34:49]
	v_mfma_f32_32x32x16_bf16 v[18:33], v[170:173], v[190:193], v[18:33]
	v_mfma_f32_32x32x16_bf16 v[2:17], v[174:177], v[190:193], v[2:17]
	s_cbranch_scc0 .LBB0_1322
	s_waitcnt vmcnt(6)
	s_barrier
	v_add_u32_e32 v0, v144, v131
	v_add_u32_e32 v164, v142, v131
	v_add_u32_e32 v165, v144, v141
	v_add_u32_e32 v190, v142, v141
	ds_read_b128 v[132:135], v0
	ds_read_b128 v[136:139], v0 offset:2048
	ds_read_b128 v[144:147], v164
	ds_read_b128 v[148:151], v164 offset:2048
	ds_read_b128 v[152:155], v164 offset:4096
	ds_read_b128 v[156:159], v164 offset:6144
	ds_read_b128 v[160:163], v165
	ds_read_b128 v[170:173], v165 offset:2048
	ds_read_b128 v[174:177], v190
	ds_read_b128 v[178:181], v190 offset:2048
	ds_read_b128 v[182:185], v190 offset:4096
	ds_read_b128 v[186:189], v190 offset:6144
	s_waitcnt lgkmcnt(0)
	v_or_b32_e32 v0, 0xa000, v143
	v_mfma_f32_32x32x16_bf16 v[114:129], v[132:135], v[144:147], v[114:129]
	s_waitcnt vmcnt(0)
	s_barrier
	s_movk_i32 s12, 0x80
	v_cmp_gt_u32_e64 s[48:49], s12, v130
	v_mfma_f32_32x32x16_bf16 v[98:113], v[136:139], v[144:147], v[98:113]
	v_mfma_f32_32x32x16_bf16 v[82:97], v[132:135], v[148:151], v[82:97]
	v_mfma_f32_32x32x16_bf16 v[66:81], v[136:139], v[148:151], v[66:81]
	v_mfma_f32_32x32x16_bf16 v[50:65], v[132:135], v[152:155], v[50:65]
	v_mfma_f32_32x32x16_bf16 v[34:49], v[136:139], v[152:155], v[34:49]
	v_mfma_f32_32x32x16_bf16 v[18:33], v[132:135], v[156:159], v[18:33]
	v_add_u32_e32 v132, 0x6000, v142
	v_mfma_f32_32x32x16_bf16 v[2:17], v[136:139], v[156:159], v[2:17]
	v_mfma_f32_32x32x16_bf16 v[114:129], v[160:163], v[174:177], v[114:129]
	v_mfma_f32_32x32x16_bf16 v[98:113], v[170:173], v[174:177], v[98:113]
	v_mfma_f32_32x32x16_bf16 v[82:97], v[160:163], v[178:181], v[82:97]
	v_mfma_f32_32x32x16_bf16 v[66:81], v[170:173], v[178:181], v[66:81]
	v_mfma_f32_32x32x16_bf16 v[50:65], v[160:163], v[182:185], v[50:65]
	v_mfma_f32_32x32x16_bf16 v[34:49], v[170:173], v[182:185], v[34:49]
	v_mfma_f32_32x32x16_bf16 v[18:33], v[160:163], v[186:189], v[18:33]
	v_mfma_f32_32x32x16_bf16 v[2:17], v[170:173], v[186:189], v[2:17]
	v_add_u32_e32 v186, v0, v131
	v_add_u32_e32 v131, v132, v131
	v_add_u32_e32 v0, v0, v141
	v_add_u32_e32 v141, v132, v141
	ds_read_b128 v[132:135], v186
	ds_read_b128 v[136:139], v186 offset:2048
	ds_read_b128 v[142:145], v131
	ds_read_b128 v[146:149], v131 offset:2048
	ds_read_b128 v[150:153], v131 offset:4096
	ds_read_b128 v[154:157], v131 offset:6144
	ds_read_b128 v[158:161], v0
	ds_read_b128 v[162:165], v0 offset:2048
	ds_read_b128 v[170:173], v141
	ds_read_b128 v[174:177], v141 offset:2048
	ds_read_b128 v[178:181], v141 offset:4096
	ds_read_b128 v[182:185], v141 offset:6144
	s_waitcnt lgkmcnt(0)
	s_waitcnt vmcnt(0) lgkmcnt(0)
	s_barrier
	v_mfma_f32_32x32x16_bf16 v[114:129], v[132:135], v[142:145], v[114:129]
	v_mfma_f32_32x32x16_bf16 v[98:113], v[136:139], v[142:145], v[98:113]
	v_and_b32_e32 v143, 64, v130
	v_and_b32_e32 v144, 31, v130
	v_mfma_f32_32x32x16_bf16 v[82:97], v[132:135], v[146:149], v[82:97]
	v_mfma_f32_32x32x16_bf16 v[66:81], v[136:139], v[146:149], v[66:81]
	v_mfma_f32_32x32x16_bf16 v[50:65], v[132:135], v[150:153], v[50:65]
	v_mfma_f32_32x32x16_bf16 v[34:49], v[136:139], v[150:153], v[34:49]
	v_mfma_f32_32x32x16_bf16 v[18:33], v[132:135], v[154:157], v[18:33]
	v_mfma_f32_32x32x16_bf16 v[2:17], v[136:139], v[154:157], v[2:17]
	v_mfma_f32_32x32x16_bf16 v[114:129], v[158:161], v[170:173], v[114:129]
	v_mfma_f32_32x32x16_bf16 v[98:113], v[162:165], v[170:173], v[98:113]
	v_mfma_f32_32x32x16_bf16 v[82:97], v[158:161], v[174:177], v[82:97]
	v_mfma_f32_32x32x16_bf16 v[66:81], v[162:165], v[174:177], v[66:81]
	v_mfma_f32_32x32x16_bf16 v[50:65], v[158:161], v[178:181], v[50:65]
	v_mfma_f32_32x32x16_bf16 v[34:49], v[162:165], v[178:181], v[34:49]
	v_mfma_f32_32x32x16_bf16 v[18:33], v[158:161], v[182:185], v[18:33]
	v_mfma_f32_32x32x16_bf16 v[2:17], v[162:165], v[182:185], v[2:17]
	s_and_saveexec_b64 s[12:13], s[48:49]
	s_cbranch_execz .LBB0_1325
	v_mul_u32_u24_e32 v0, 0x210, v144
	v_lshlrev_b32_e32 v131, 4, v140
	v_lshlrev_b32_e32 v132, 2, v143
	v_add3_u32 v0, v0, v131, v132
	ds_write_b128 v0, v[114:117]
	ds_write_b128 v0, v[118:121] offset:32
	ds_write_b128 v0, v[122:125] offset:64
	ds_write_b128 v0, v[126:129] offset:96
	ds_write_b128 v0, v[98:101] offset:128
	ds_write_b128 v0, v[102:105] offset:160
	ds_write_b128 v0, v[106:109] offset:192
	ds_write_b128 v0, v[110:113] offset:224
	ds_write_b128 v0, v[82:85] offset:16896
	ds_write_b128 v0, v[86:89] offset:16928
	ds_write_b128 v0, v[90:93] offset:16960
	ds_write_b128 v0, v[94:97] offset:16992
	ds_write_b128 v0, v[66:69] offset:17024
	ds_write_b128 v0, v[70:73] offset:17056
	ds_write_b128 v0, v[74:77] offset:17088
	ds_write_b128 v0, v[78:81] offset:17120
	ds_write_b128 v0, v[50:53] offset:33792
	ds_write_b128 v0, v[54:57] offset:33824
	ds_write_b128 v0, v[58:61] offset:33856
	ds_write_b128 v0, v[62:65] offset:33888
	ds_write_b128 v0, v[34:37] offset:33920
	ds_write_b128 v0, v[38:41] offset:33952
	ds_write_b128 v0, v[42:45] offset:33984
	ds_write_b128 v0, v[46:49] offset:34016
	v_or_b32_e32 v0, 0x60, v130
	v_mul_lo_u32 v0, v0, s94
	v_add3_u32 v0, v0, v131, v132
	ds_write_b128 v0, v[18:21]
	ds_write_b128 v0, v[22:25] offset:32
	ds_write_b128 v0, v[26:29] offset:64
	ds_write_b128 v0, v[30:33] offset:96
	ds_write_b128 v0, v[2:5] offset:128
	ds_write_b128 v0, v[6:9] offset:160
	ds_write_b128 v0, v[10:13] offset:192
	ds_write_b128 v0, v[14:17] offset:224

.LBB0_1421:
	s_mul_i32 s21, s20, 0x6000
	v_add_u32_e32 v146, s21, v145
	v_add_u32_e32 v147, s21, v143
	v_add_u32_e32 v198, v146, v141
	v_add_u32_e32 v199, v147, v141
	v_add_u32_e32 v200, v146, v142
	v_add_u32_e32 v201, v147, v142
	s_waitcnt vmcnt(6)
	s_barrier
	ds_read_b128 v[146:149], v198
	ds_read_b128 v[150:153], v198 offset:2048
	ds_read_b128 v[154:157], v199
	ds_read_b128 v[158:161], v199 offset:2048
	ds_read_b128 v[162:165], v199 offset:4096
	ds_read_b128 v[170:173], v199 offset:6144
	ds_read_b128 v[174:177], v200
	ds_read_b128 v[178:181], v200 offset:2048
	ds_read_b128 v[182:185], v201
	ds_read_b128 v[186:189], v201 offset:2048
	ds_read_b128 v[190:193], v201 offset:4096
	ds_read_b128 v[194:197], v201 offset:6144
	s_waitcnt lgkmcnt(0)
	v_mfma_f32_32x32x16_bf16 v[114:129], v[146:149], v[154:157], v[114:129]
	v_mfma_f32_32x32x16_bf16 v[82:97], v[146:149], v[158:161], v[82:97]
	v_mfma_f32_32x32x16_bf16 v[50:65], v[146:149], v[162:165], v[50:65]
	v_mfma_f32_32x32x16_bf16 v[18:33], v[146:149], v[170:173], v[18:33]
	s_add_i32 s22, s21, 0xffffa000
	s_cmp_gt_i32 s20, 0
	s_cselect_b32 s22, s22, 0xc000
	v_add_u32_e32 v148, s22, v139
	v_lshl_add_u64 v[136:137], v[132:133], 0, v[0:1]
	v_readfirstlane_b32 s22, v148
	v_add_u32_e32 v146, 0x1000, v148
	v_lshl_add_u64 v[134:135], v[136:137], 0, s[34:35]
	s_mov_b32 m0, s22
	v_readfirstlane_b32 s22, v146
	v_add_u32_e32 v146, 0x2000, v148
	global_load_lds_dwordx4 v[134:135], off
	v_mfma_f32_32x32x16_bf16 v[98:113], v[150:153], v[154:157], v[98:113]
	v_lshl_add_u64 v[134:135], v[136:137], 0, s[36:37]
	s_mov_b32 m0, s22
	v_readfirstlane_b32 s22, v146
	v_add_u32_e32 v146, 0x3000, v148
	global_load_lds_dwordx4 v[134:135], off
	v_mfma_f32_32x32x16_bf16 v[66:81], v[150:153], v[158:161], v[66:81]
	v_lshl_add_u64 v[134:135], v[136:137], 0, s[24:25]
	s_mov_b32 m0, s22
	v_readfirstlane_b32 s22, v146
	global_load_lds_dwordx4 v[134:135], off
	v_mfma_f32_32x32x16_bf16 v[34:49], v[150:153], v[162:165], v[34:49]
	v_lshl_add_u64 v[134:135], v[136:137], 0, s[38:39]
	s_mov_b32 m0, s22
	s_mov_b64 s[22:23], 0x920000
	global_load_lds_dwordx4 v[134:135], off
	v_mfma_f32_32x32x16_bf16 v[2:17], v[150:153], v[170:173], v[2:17]
	v_lshl_add_u64 v[134:135], v[130:131], 0, v[0:1]
	v_add_u32_e32 v149, 0x4000, v148
	v_lshl_add_u64 v[146:147], v[134:135], 0, s[22:23]
	v_readfirstlane_b32 s22, v149
	s_mov_b32 m0, s22
	s_mov_b64 s[22:23], 0x921000
	v_add_u32_e32 v148, 0x5000, v148
	global_load_lds_dwordx4 v[146:147], off
	v_mfma_f32_32x32x16_bf16 v[114:129], v[174:177], v[182:185], v[114:129]
	v_lshl_add_u64 v[146:147], v[134:135], 0, s[22:23]
	v_readfirstlane_b32 s22, v148
	s_mov_b32 m0, s22
	v_lshl_add_u64 v[130:131], v[130:131], 0, s[58:59]
	global_load_lds_dwordx4 v[146:147], off
	v_mfma_f32_32x32x16_bf16 v[98:113], v[178:181], v[182:185], v[98:113]
	s_waitcnt vmcnt(6)
	s_barrier
	s_add_i32 s21, s20, 1
	s_cmp_lg_u32 s20, 2
	s_cselect_b32 s20, s21, 0
	s_mul_i32 s21, s20, 0x6000
	s_add_i32 s22, s21, 0xffffa000
	s_cmp_gt_i32 s20, 0
	s_cselect_b32 s22, s22, 0xc000
	v_lshl_add_u64 v[132:133], v[132:133], 0, s[96:97]
	v_add_u32_e32 v148, s22, v139
	v_add_u32_e32 v149, 0x1000, v148
	v_readfirstlane_b32 s22, v148
	v_lshl_add_u64 v[146:147], v[136:137], 0, s[88:89]
	s_mov_b32 m0, s22
	v_readfirstlane_b32 s22, v149
	v_add_u32_e32 v149, 0x2000, v148
	global_load_lds_dwordx4 v[146:147], off
	v_mfma_f32_32x32x16_bf16 v[82:97], v[174:177], v[186:189], v[82:97]
	v_lshl_add_u64 v[146:147], v[136:137], 0, s[4:5]
	s_mov_b32 m0, s22
	v_readfirstlane_b32 s22, v149
	global_load_lds_dwordx4 v[146:147], off
	v_mfma_f32_32x32x16_bf16 v[66:81], v[178:181], v[186:189], v[66:81]
	v_lshl_add_u64 v[146:147], v[136:137], 0, s[84:85]
	s_mov_b32 m0, s22
	v_lshl_add_u64 v[136:137], v[136:137], 0, s[86:87]
	global_load_lds_dwordx4 v[146:147], off
	v_mfma_f32_32x32x16_bf16 v[50:65], v[174:177], v[190:193], v[50:65]
	v_add_u32_e32 v146, 0x3000, v148
	s_nop 0
	v_readfirstlane_b32 s22, v146
	s_mov_b32 m0, s22
	s_mov_b64 s[22:23], 0x930000
	v_add_u32_e32 v146, 0x4000, v148
	global_load_lds_dwordx4 v[136:137], off
	v_mfma_f32_32x32x16_bf16 v[34:49], v[178:181], v[190:193], v[34:49]
	v_lshl_add_u64 v[136:137], v[134:135], 0, s[22:23]
	v_readfirstlane_b32 s22, v146
	s_mov_b32 m0, s22
	s_mov_b64 s[22:23], 0x931000
	global_load_lds_dwordx4 v[136:137], off
	v_mfma_f32_32x32x16_bf16 v[18:33], v[174:177], v[194:197], v[18:33]
	v_add_u32_e32 v136, 0x5000, v148
	v_lshl_add_u64 v[134:135], v[134:135], 0, s[22:23]
	v_readfirstlane_b32 s22, v136
	s_mov_b32 m0, s22
	s_nop 0
	global_load_lds_dwordx4 v[134:135], off
	v_mfma_f32_32x32x16_bf16 v[2:17], v[178:181], v[194:197], v[2:17]
	v_add_u32_e32 v134, s21, v145
	v_add_u32_e32 v135, s21, v143
	s_add_i32 s21, s20, 1
	s_cmp_lg_u32 s20, 2
	s_cselect_b32 s20, s21, 0
	s_add_i32 s19, s19, -2
	s_cmp_eq_u32 s19, 0
	v_add_u32_e32 v194, v134, v141
	v_add_u32_e32 v195, v135, v141
	v_add_u32_e32 v196, v134, v142
	v_add_u32_e32 v197, v135, v142
	ds_read_b128 v[134:137], v194
	ds_read_b128 v[146:149], v194 offset:2048
	ds_read_b128 v[150:153], v195
	ds_read_b128 v[154:157], v195 offset:2048
	ds_read_b128 v[158:161], v195 offset:4096
	ds_read_b128 v[162:165], v195 offset:6144
	ds_read_b128 v[170:173], v196
	ds_read_b128 v[174:177], v196 offset:2048
	ds_read_b128 v[178:181], v197
	ds_read_b128 v[182:185], v197 offset:2048
	ds_read_b128 v[186:189], v197 offset:4096
	ds_read_b128 v[190:193], v197 offset:6144
	s_waitcnt lgkmcnt(0)
	s_nop 0
	v_mfma_f32_32x32x16_bf16 v[114:129], v[134:137], v[150:153], v[114:129]
	v_mfma_f32_32x32x16_bf16 v[98:113], v[146:149], v[150:153], v[98:113]
	v_mfma_f32_32x32x16_bf16 v[82:97], v[134:137], v[154:157], v[82:97]
	v_mfma_f32_32x32x16_bf16 v[66:81], v[146:149], v[154:157], v[66:81]
	v_mfma_f32_32x32x16_bf16 v[50:65], v[134:137], v[158:161], v[50:65]
	v_mfma_f32_32x32x16_bf16 v[34:49], v[146:149], v[158:161], v[34:49]
	v_mfma_f32_32x32x16_bf16 v[18:33], v[134:137], v[162:165], v[18:33]
	v_mfma_f32_32x32x16_bf16 v[2:17], v[146:149], v[162:165], v[2:17]
	v_mfma_f32_32x32x16_bf16 v[114:129], v[170:173], v[178:181], v[114:129]
	v_mfma_f32_32x32x16_bf16 v[98:113], v[174:177], v[178:181], v[98:113]
	v_mfma_f32_32x32x16_bf16 v[82:97], v[170:173], v[182:185], v[82:97]
	v_mfma_f32_32x32x16_bf16 v[66:81], v[174:177], v[182:185], v[66:81]
	v_mfma_f32_32x32x16_bf16 v[50:65], v[170:173], v[186:189], v[50:65]
	v_mfma_f32_32x32x16_bf16 v[34:49], v[174:177], v[186:189], v[34:49]
	v_mfma_f32_32x32x16_bf16 v[18:33], v[170:173], v[190:193], v[18:33]
	v_mfma_f32_32x32x16_bf16 v[2:17], v[174:177], v[190:193], v[2:17]
	s_cbranch_scc0 .LBB0_1421
	s_waitcnt vmcnt(6)
	s_barrier
	v_add_u32_e32 v0, v145, v141
	v_add_u32_e32 v190, v143, v141
	v_add_u32_e32 v145, v145, v142
	v_add_u32_e32 v191, v143, v142
	ds_read_b128 v[130:133], v0
	ds_read_b128 v[134:137], v0 offset:2048
	ds_read_b128 v[146:149], v190
	ds_read_b128 v[150:153], v190 offset:2048
	ds_read_b128 v[154:157], v190 offset:4096
	ds_read_b128 v[158:161], v190 offset:6144
	ds_read_b128 v[162:165], v145
	ds_read_b128 v[170:173], v145 offset:2048
	ds_read_b128 v[174:177], v191
	ds_read_b128 v[178:181], v191 offset:2048
	ds_read_b128 v[182:185], v191 offset:4096
	ds_read_b128 v[186:189], v191 offset:6144
	s_waitcnt lgkmcnt(0)
	v_or_b32_e32 v0, 0xa000, v144
	v_mfma_f32_32x32x16_bf16 v[50:65], v[130:133], v[154:157], v[50:65]
	s_waitcnt vmcnt(0)
	s_barrier
	v_add_u32_e32 v190, v141, v0
	v_add_u32_e32 v0, v142, v0
	s_lshl_b32 s19, s17, 9
	s_and_b32 s19, s19, 0xc00
	s_lshr_b32 s18, s18, 5
	v_mfma_f32_32x32x16_bf16 v[34:49], v[134:137], v[154:157], v[34:49]
	s_add_i32 s18, s18, s19
	s_lshl_b32 s19, s17, 3
	s_and_b32 s19, s19, 8
	v_mfma_f32_32x32x16_bf16 v[82:97], v[130:133], v[150:153], v[82:97]
	v_mfma_f32_32x32x16_bf16 v[66:81], v[134:137], v[150:153], v[66:81]
	v_mfma_f32_32x32x16_bf16 v[2:17], v[134:137], v[158:161], v[2:17]
	v_mfma_f32_32x32x16_bf16 v[114:129], v[130:133], v[146:149], v[114:129]
	v_mfma_f32_32x32x16_bf16 v[98:113], v[134:137], v[146:149], v[98:113]
	v_mfma_f32_32x32x16_bf16 v[18:33], v[130:133], v[158:161], v[18:33]
	v_add_u32_e32 v130, 0x6000, v143
	v_add_u32_e32 v141, v141, v130
	v_mfma_f32_32x32x16_bf16 v[50:65], v[162:165], v[182:185], v[50:65]
	v_mfma_f32_32x32x16_bf16 v[34:49], v[170:173], v[182:185], v[34:49]
	v_mfma_f32_32x32x16_bf16 v[82:97], v[162:165], v[178:181], v[82:97]
	v_mfma_f32_32x32x16_bf16 v[66:81], v[170:173], v[178:181], v[66:81]
	v_mfma_f32_32x32x16_bf16 v[2:17], v[170:173], v[186:189], v[2:17]
	v_mfma_f32_32x32x16_bf16 v[114:129], v[162:165], v[174:177], v[114:129]
	v_mfma_f32_32x32x16_bf16 v[98:113], v[170:173], v[174:177], v[98:113]
	v_mfma_f32_32x32x16_bf16 v[18:33], v[162:165], v[186:189], v[18:33]
	v_add_u32_e32 v186, v142, v130
	ds_read_b128 v[130:133], v190
	ds_read_b128 v[134:137], v190 offset:2048
	ds_read_b128 v[142:145], v141
	ds_read_b128 v[146:149], v141 offset:2048
	ds_read_b128 v[150:153], v141 offset:4096
	ds_read_b128 v[154:157], v141 offset:6144
	ds_read_b128 v[158:161], v0
	ds_read_b128 v[162:165], v0 offset:2048
	ds_read_b128 v[170:173], v186
	ds_read_b128 v[174:177], v186 offset:2048
	ds_read_b128 v[178:181], v186 offset:4096
	ds_read_b128 v[182:185], v186 offset:6144
	s_waitcnt lgkmcnt(0)
	v_lshlrev_b32_e32 v0, 1, v138
	v_and_b32_e32 v0, 0x80, v0
	v_and_b32_e32 v141, 0xfffff9f, v138
	v_lshl_or_b32 v0, v140, 3, v0
	v_mad_u64_u32 v[140:141], s[20:21], v141, s3, v[0:1]
	v_mfma_f32_32x32x16_bf16 v[50:65], v[130:133], v[150:153], v[50:65]
	s_waitcnt vmcnt(0) lgkmcnt(0)
	s_barrier
	v_mfma_f32_32x32x16_bf16 v[34:49], v[134:137], v[150:153], v[34:49]
	v_mfma_f32_32x32x16_bf16 v[82:97], v[130:133], v[146:149], v[82:97]
	v_mfma_f32_32x32x16_bf16 v[66:81], v[134:137], v[146:149], v[66:81]
	v_mfma_f32_32x32x16_bf16 v[2:17], v[134:137], v[154:157], v[2:17]
	v_mfma_f32_32x32x16_bf16 v[114:129], v[130:133], v[142:145], v[114:129]
	v_mfma_f32_32x32x16_bf16 v[98:113], v[134:137], v[142:145], v[98:113]
	v_mfma_f32_32x32x16_bf16 v[18:33], v[130:133], v[154:157], v[18:33]
	v_mfma_f32_32x32x16_bf16 v[50:65], v[158:161], v[178:181], v[50:65]
	v_mfma_f32_32x32x16_bf16 v[34:49], v[162:165], v[178:181], v[34:49]
	s_nop 10
	v_cvt_pk_bf16_f32 v50, v50, v51
	v_cvt_pk_bf16_f32 v51, v52, v53
	v_cvt_pk_bf16_f32 v52, v54, v55
	v_add_u32_e32 v54, 0x4000, v140
	v_cvt_pk_bf16_f32 v53, v56, v57
	ds_write2_b64 v54, v[50:51], v[52:53] offset0:128 offset1:130
	v_cvt_pk_bf16_f32 v50, v58, v59
	v_mfma_f32_32x32x16_bf16 v[82:97], v[158:161], v[174:177], v[82:97]
	v_cvt_pk_bf16_f32 v34, v34, v35
	v_cvt_pk_bf16_f32 v35, v36, v37
	v_cvt_pk_bf16_f32 v36, v38, v39
	v_cvt_pk_bf16_f32 v37, v40, v41
	ds_write2_b64 v54, v[34:35], v[36:37] offset0:136 offset1:138
	v_cvt_pk_bf16_f32 v34, v42, v43
	v_cvt_pk_bf16_f32 v35, v44, v45
	v_mfma_f32_32x32x16_bf16 v[66:81], v[162:165], v[174:177], v[66:81]
	v_cvt_pk_bf16_f32 v36, v46, v47
	v_cvt_pk_bf16_f32 v37, v48, v49
	ds_write2_b64 v54, v[34:35], v[36:37] offset0:140 offset1:142
	v_or_b32_e32 v34, 0x60, v138
	v_cvt_pk_bf16_f32 v82, v82, v83
	v_cvt_pk_bf16_f32 v83, v84, v85
	v_cvt_pk_bf16_f32 v84, v86, v87
	v_mfma_f32_32x32x16_bf16 v[2:17], v[162:165], v[182:185], v[2:17]
	v_add_u32_e32 v86, 0x2000, v140
	s_nop 2
	v_cvt_pk_bf16_f32 v66, v66, v67
	v_cvt_pk_bf16_f32 v67, v68, v69
	v_cvt_pk_bf16_f32 v68, v70, v71
	v_cvt_pk_bf16_f32 v69, v72, v73
	v_mad_u64_u32 v[34:35], s[20:21], v34, s3, v[0:1]
	v_mfma_f32_32x32x16_bf16 v[114:129], v[158:161], v[170:173], v[114:129]
	s_nop 1
	v_cvt_pk_bf16_f32 v2, v2, v3
	v_cvt_pk_bf16_f32 v3, v4, v5
	v_cvt_pk_bf16_f32 v4, v6, v7
	v_cvt_pk_bf16_f32 v5, v8, v9
	v_lshrrev_b32_e32 v0, 1, v138
	ds_write2_b64 v86, v[66:67], v[68:69] offset0:72 offset1:74
	v_cvt_pk_bf16_f32 v66, v74, v75
	v_mfma_f32_32x32x16_bf16 v[98:113], v[162:165], v[170:173], v[98:113]
	v_cvt_pk_bf16_f32 v67, v76, v77
	v_cvt_pk_bf16_f32 v68, v78, v79
	v_cvt_pk_bf16_f32 v69, v80, v81
	ds_write2_b64 v34, v[2:3], v[4:5] offset0:8 offset1:10
	v_cvt_pk_bf16_f32 v2, v10, v11
	v_cvt_pk_bf16_f32 v3, v12, v13
	v_cvt_pk_bf16_f32 v4, v14, v15
	v_mfma_f32_32x32x16_bf16 v[18:33], v[158:161], v[182:185], v[18:33]
	v_cvt_pk_bf16_f32 v5, v16, v17
	v_and_b32_e32 v8, 16, v0
	v_and_b32_e32 v0, 0x3f0, v139
	ds_write2_b64 v86, v[66:67], v[68:69] offset0:76 offset1:78
	ds_write2_b64 v34, v[2:3], v[4:5] offset0:12 offset1:14
	v_lshl_add_u64 v[2:3], s[92:93], 0, v[0:1]
	v_bfe_u32 v0, v138, 6, 3
	v_lshl_or_b32 v4, v0, 5, v8
	v_or_b32_e32 v0, s19, v0
	v_cvt_pk_bf16_f32 v114, v114, v115
	v_cvt_pk_bf16_f32 v115, v116, v117
	v_cvt_pk_bf16_f32 v116, v118, v119
	v_cvt_pk_bf16_f32 v117, v120, v121
	v_cvt_pk_bf16_f32 v98, v98, v99
	v_cvt_pk_bf16_f32 v99, v100, v101
	v_cvt_pk_bf16_f32 v100, v102, v103
	v_cvt_pk_bf16_f32 v101, v104, v105
	v_cvt_pk_bf16_f32 v85, v88, v89
	v_cvt_pk_bf16_f32 v18, v18, v19
	v_cvt_pk_bf16_f32 v19, v20, v21
	v_cvt_pk_bf16_f32 v20, v22, v23
	v_cvt_pk_bf16_f32 v21, v24, v25
	v_lshlrev_b32_e32 v0, 10, v0
	ds_write2_b64 v140, v[114:115], v[116:117] offset1:2
	v_cvt_pk_bf16_f32 v114, v122, v123
	v_cvt_pk_bf16_f32 v115, v124, v125
	v_cvt_pk_bf16_f32 v116, v126, v127
	v_cvt_pk_bf16_f32 v117, v128, v129
	ds_write2_b64 v140, v[98:99], v[100:101] offset0:8 offset1:10
	v_cvt_pk_bf16_f32 v98, v106, v107
	v_cvt_pk_bf16_f32 v99, v108, v109
	v_cvt_pk_bf16_f32 v100, v110, v111
	v_cvt_pk_bf16_f32 v101, v112, v113
	ds_write2_b64 v86, v[82:83], v[84:85] offset0:64 offset1:66
	v_cvt_pk_bf16_f32 v82, v90, v91
	v_cvt_pk_bf16_f32 v83, v92, v93
	v_cvt_pk_bf16_f32 v84, v94, v95
	v_cvt_pk_bf16_f32 v85, v96, v97
	v_cvt_pk_bf16_f32 v51, v60, v61
	v_cvt_pk_bf16_f32 v52, v62, v63
	v_cvt_pk_bf16_f32 v53, v64, v65
	ds_write2_b64 v34, v[18:19], v[20:21] offset1:2
	v_cvt_pk_bf16_f32 v18, v26, v27
	v_cvt_pk_bf16_f32 v19, v28, v29
	v_cvt_pk_bf16_f32 v20, v30, v31
	v_cvt_pk_bf16_f32 v21, v32, v33
	v_and_b32_e32 v5, 31, v138
	v_lshl_add_u64 v[6:7], v[2:3], 0, v[0:1]
	s_mov_b32 s20, 0
	ds_write2_b64 v140, v[114:115], v[116:117] offset0:4 offset1:6
	ds_write2_b64 v140, v[98:99], v[100:101] offset0:12 offset1:14
	ds_write2_b64 v86, v[82:83], v[84:85] offset0:68 offset1:70
	ds_write2_b64 v54, v[50:51], v[52:53] offset0:132 offset1:134
	ds_write2_b64 v34, v[18:19], v[20:21] offset0:4 offset1:6
	s_waitcnt lgkmcnt(0)
	s_barrier

.LBB0_1555:
	s_mul_i32 s16, s13, 0x6000
	v_add_u32_e32 v146, s16, v144
	v_add_u32_e32 v147, s16, v142
	v_add_u32_e32 v198, v146, v131
	v_add_u32_e32 v199, v147, v131
	v_add_u32_e32 v200, v146, v141
	v_add_u32_e32 v201, v147, v141
	s_waitcnt vmcnt(6)
	s_barrier
	ds_read_b128 v[146:149], v198
	ds_read_b128 v[150:153], v198 offset:2048
	ds_read_b128 v[154:157], v199
	ds_read_b128 v[158:161], v199 offset:2048
	ds_read_b128 v[162:165], v199 offset:4096
	ds_read_b128 v[170:173], v199 offset:6144
	ds_read_b128 v[174:177], v200
	ds_read_b128 v[178:181], v200 offset:2048
	ds_read_b128 v[182:185], v201
	ds_read_b128 v[186:189], v201 offset:2048
	ds_read_b128 v[190:193], v201 offset:4096
	ds_read_b128 v[194:197], v201 offset:6144
	s_waitcnt lgkmcnt(0)
	v_mfma_f32_32x32x16_bf16 v[114:129], v[146:149], v[154:157], v[114:129]
	v_mfma_f32_32x32x16_bf16 v[82:97], v[146:149], v[158:161], v[82:97]
	v_mfma_f32_32x32x16_bf16 v[50:65], v[146:149], v[162:165], v[50:65]
	v_mfma_f32_32x32x16_bf16 v[18:33], v[146:149], v[170:173], v[18:33]
	s_add_i32 s14, s16, 0xffffa000
	s_cmp_gt_i32 s13, 0
	s_cselect_b32 s14, s14, 0xc000
	v_add_u32_e32 v148, s14, v145
	v_lshl_add_u64 v[138:139], v[134:135], 0, v[0:1]
	v_readfirstlane_b32 s14, v148
	v_add_u32_e32 v146, 0x1000, v148
	v_lshl_add_u64 v[136:137], v[138:139], 0, s[18:19]
	s_mov_b32 m0, s14
	v_readfirstlane_b32 s14, v146
	v_add_u32_e32 v146, 0x2000, v148
	global_load_lds_dwordx4 v[136:137], off
	v_mfma_f32_32x32x16_bf16 v[98:113], v[150:153], v[154:157], v[98:113]
	v_lshl_add_u64 v[136:137], v[138:139], 0, s[20:21]
	s_mov_b32 m0, s14
	v_readfirstlane_b32 s14, v146
	v_add_u32_e32 v146, 0x3000, v148
	global_load_lds_dwordx4 v[136:137], off
	v_mfma_f32_32x32x16_bf16 v[66:81], v[150:153], v[158:161], v[66:81]
	v_lshl_add_u64 v[136:137], v[138:139], 0, s[40:41]
	s_mov_b32 m0, s14
	v_readfirstlane_b32 s14, v146
	global_load_lds_dwordx4 v[136:137], off
	v_mfma_f32_32x32x16_bf16 v[34:49], v[150:153], v[162:165], v[34:49]
	v_lshl_add_u64 v[136:137], v[138:139], 0, s[42:43]
	s_mov_b32 m0, s14
	s_mov_b64 s[14:15], 0xf20000
	global_load_lds_dwordx4 v[136:137], off
	v_mfma_f32_32x32x16_bf16 v[2:17], v[150:153], v[170:173], v[2:17]
	v_lshl_add_u64 v[136:137], v[132:133], 0, v[0:1]
	v_add_u32_e32 v149, 0x4000, v148
	v_lshl_add_u64 v[146:147], v[136:137], 0, s[14:15]
	v_readfirstlane_b32 s14, v149
	s_mov_b32 m0, s14
	s_mov_b64 s[14:15], 0xf21000
	v_add_u32_e32 v148, 0x5000, v148
	global_load_lds_dwordx4 v[146:147], off
	v_mfma_f32_32x32x16_bf16 v[114:129], v[174:177], v[182:185], v[114:129]
	v_lshl_add_u64 v[146:147], v[136:137], 0, s[14:15]
	v_readfirstlane_b32 s14, v148
	s_mov_b32 m0, s14
	s_add_i32 s14, s13, 1
	s_cmp_lg_u32 s13, 2
	s_cselect_b32 s13, s14, 0
	s_mul_i32 s14, s13, 0x6000
	s_add_i32 s15, s14, 0xffffa000
	global_load_lds_dwordx4 v[146:147], off
	v_mfma_f32_32x32x16_bf16 v[98:113], v[178:181], v[182:185], v[98:113]
	s_waitcnt vmcnt(6)
	s_barrier
	s_cmp_gt_i32 s13, 0
	s_cselect_b32 s15, s15, 0xc000
	s_mov_b64 s[16:17], 0xf30000
	v_lshl_add_u64 v[132:133], v[132:133], 0, s[58:59]
	v_lshl_add_u64 v[134:135], v[134:135], 0, s[96:97]
	v_add_u32_e32 v148, s15, v145
	v_add_u32_e32 v149, 0x1000, v148
	v_readfirstlane_b32 s15, v148
	v_lshl_add_u64 v[146:147], v[138:139], 0, s[46:47]
	s_mov_b32 m0, s15
	v_readfirstlane_b32 s15, v149
	v_add_u32_e32 v149, 0x2000, v148
	global_load_lds_dwordx4 v[146:147], off
	v_mfma_f32_32x32x16_bf16 v[82:97], v[174:177], v[186:189], v[82:97]
	v_lshl_add_u64 v[146:147], v[138:139], 0, s[48:49]
	s_mov_b32 m0, s15
	v_readfirstlane_b32 s15, v149
	global_load_lds_dwordx4 v[146:147], off
	v_mfma_f32_32x32x16_bf16 v[66:81], v[178:181], v[186:189], v[66:81]
	v_lshl_add_u64 v[146:147], v[138:139], 0, s[50:51]
	s_mov_b32 m0, s15
	v_lshl_add_u64 v[138:139], v[138:139], 0, s[56:57]
	global_load_lds_dwordx4 v[146:147], off
	v_mfma_f32_32x32x16_bf16 v[50:65], v[174:177], v[190:193], v[50:65]
	v_add_u32_e32 v146, 0x3000, v148
	s_nop 0
	v_readfirstlane_b32 s15, v146
	v_add_u32_e32 v146, 0x4000, v148
	s_mov_b32 m0, s15
	v_readfirstlane_b32 s15, v146
	global_load_lds_dwordx4 v[138:139], off
	v_mfma_f32_32x32x16_bf16 v[34:49], v[178:181], v[190:193], v[34:49]
	v_lshl_add_u64 v[138:139], v[136:137], 0, s[16:17]
	s_mov_b32 m0, s15
	s_mov_b64 s[16:17], 0xf31000
	global_load_lds_dwordx4 v[138:139], off
	v_mfma_f32_32x32x16_bf16 v[18:33], v[174:177], v[194:197], v[18:33]
	v_add_u32_e32 v138, 0x5000, v148
	v_lshl_add_u64 v[136:137], v[136:137], 0, s[16:17]
	v_readfirstlane_b32 s15, v138
	s_mov_b32 m0, s15
	s_nop 0
	global_load_lds_dwordx4 v[136:137], off
	v_mfma_f32_32x32x16_bf16 v[2:17], v[178:181], v[194:197], v[2:17]
	v_add_u32_e32 v136, s14, v144
	v_add_u32_e32 v137, s14, v142
	s_add_i32 s14, s13, 1
	s_cmp_lg_u32 s13, 2
	s_cselect_b32 s13, s14, 0
	s_add_i32 s12, s12, -2
	s_cmp_eq_u32 s12, 0
	v_add_u32_e32 v194, v136, v131
	v_add_u32_e32 v195, v137, v131
	v_add_u32_e32 v196, v136, v141
	v_add_u32_e32 v197, v137, v141
	ds_read_b128 v[136:139], v194
	ds_read_b128 v[146:149], v194 offset:2048
	ds_read_b128 v[150:153], v195
	ds_read_b128 v[154:157], v195 offset:2048
	ds_read_b128 v[158:161], v195 offset:4096
	ds_read_b128 v[162:165], v195 offset:6144
	ds_read_b128 v[170:173], v196
	ds_read_b128 v[174:177], v196 offset:2048
	ds_read_b128 v[178:181], v197
	ds_read_b128 v[182:185], v197 offset:2048
	ds_read_b128 v[186:189], v197 offset:4096
	ds_read_b128 v[190:193], v197 offset:6144
	s_waitcnt lgkmcnt(0)
	s_nop 0
	v_mfma_f32_32x32x16_bf16 v[114:129], v[136:139], v[150:153], v[114:129]
	v_mfma_f32_32x32x16_bf16 v[98:113], v[146:149], v[150:153], v[98:113]
	v_mfma_f32_32x32x16_bf16 v[82:97], v[136:139], v[154:157], v[82:97]
	v_mfma_f32_32x32x16_bf16 v[66:81], v[146:149], v[154:157], v[66:81]
	v_mfma_f32_32x32x16_bf16 v[50:65], v[136:139], v[158:161], v[50:65]
	v_mfma_f32_32x32x16_bf16 v[34:49], v[146:149], v[158:161], v[34:49]
	v_mfma_f32_32x32x16_bf16 v[18:33], v[136:139], v[162:165], v[18:33]
	v_mfma_f32_32x32x16_bf16 v[2:17], v[146:149], v[162:165], v[2:17]
	v_mfma_f32_32x32x16_bf16 v[114:129], v[170:173], v[178:181], v[114:129]
	v_mfma_f32_32x32x16_bf16 v[98:113], v[174:177], v[178:181], v[98:113]
	v_mfma_f32_32x32x16_bf16 v[82:97], v[170:173], v[182:185], v[82:97]
	v_mfma_f32_32x32x16_bf16 v[66:81], v[174:177], v[182:185], v[66:81]
	v_mfma_f32_32x32x16_bf16 v[50:65], v[170:173], v[186:189], v[50:65]
	v_mfma_f32_32x32x16_bf16 v[34:49], v[174:177], v[186:189], v[34:49]
	v_mfma_f32_32x32x16_bf16 v[18:33], v[170:173], v[190:193], v[18:33]
	v_mfma_f32_32x32x16_bf16 v[2:17], v[174:177], v[190:193], v[2:17]
	s_cbranch_scc0 .LBB0_1555
	s_waitcnt vmcnt(6)
	s_barrier
	v_add_u32_e32 v0, v144, v131
	v_add_u32_e32 v164, v142, v131
	v_add_u32_e32 v165, v144, v141
	v_add_u32_e32 v190, v142, v141
	ds_read_b128 v[132:135], v0
	ds_read_b128 v[136:139], v0 offset:2048
	ds_read_b128 v[144:147], v164
	ds_read_b128 v[148:151], v164 offset:2048
	ds_read_b128 v[152:155], v164 offset:4096
	ds_read_b128 v[156:159], v164 offset:6144
	ds_read_b128 v[160:163], v165
	ds_read_b128 v[170:173], v165 offset:2048
	ds_read_b128 v[174:177], v190
	ds_read_b128 v[178:181], v190 offset:2048
	ds_read_b128 v[182:185], v190 offset:4096
	ds_read_b128 v[186:189], v190 offset:6144
	s_waitcnt lgkmcnt(0)
	v_or_b32_e32 v0, 0xa000, v143
	v_mfma_f32_32x32x16_bf16 v[114:129], v[132:135], v[144:147], v[114:129]
	s_waitcnt vmcnt(0)
	s_barrier
	s_movk_i32 s12, 0x80
	v_cmp_gt_u32_e64 s[48:49], s12, v130
	v_mfma_f32_32x32x16_bf16 v[98:113], v[136:139], v[144:147], v[98:113]
	v_mfma_f32_32x32x16_bf16 v[82:97], v[132:135], v[148:151], v[82:97]
	v_mfma_f32_32x32x16_bf16 v[66:81], v[136:139], v[148:151], v[66:81]
	v_mfma_f32_32x32x16_bf16 v[50:65], v[132:135], v[152:155], v[50:65]
	v_mfma_f32_32x32x16_bf16 v[34:49], v[136:139], v[152:155], v[34:49]
	v_mfma_f32_32x32x16_bf16 v[18:33], v[132:135], v[156:159], v[18:33]
	v_add_u32_e32 v132, 0x6000, v142
	v_mfma_f32_32x32x16_bf16 v[2:17], v[136:139], v[156:159], v[2:17]
	v_mfma_f32_32x32x16_bf16 v[114:129], v[160:163], v[174:177], v[114:129]
	v_mfma_f32_32x32x16_bf16 v[98:113], v[170:173], v[174:177], v[98:113]
	v_mfma_f32_32x32x16_bf16 v[82:97], v[160:163], v[178:181], v[82:97]
	v_mfma_f32_32x32x16_bf16 v[66:81], v[170:173], v[178:181], v[66:81]
	v_mfma_f32_32x32x16_bf16 v[50:65], v[160:163], v[182:185], v[50:65]
	v_mfma_f32_32x32x16_bf16 v[34:49], v[170:173], v[182:185], v[34:49]
	v_mfma_f32_32x32x16_bf16 v[18:33], v[160:163], v[186:189], v[18:33]
	v_mfma_f32_32x32x16_bf16 v[2:17], v[170:173], v[186:189], v[2:17]
	v_add_u32_e32 v186, v0, v131
	v_add_u32_e32 v131, v132, v131
	v_add_u32_e32 v0, v0, v141
	v_add_u32_e32 v141, v132, v141
	ds_read_b128 v[132:135], v186
	ds_read_b128 v[136:139], v186 offset:2048
	ds_read_b128 v[142:145], v131
	ds_read_b128 v[146:149], v131 offset:2048
	ds_read_b128 v[150:153], v131 offset:4096
	ds_read_b128 v[154:157], v131 offset:6144
	ds_read_b128 v[158:161], v0
	ds_read_b128 v[162:165], v0 offset:2048
	ds_read_b128 v[170:173], v141
	ds_read_b128 v[174:177], v141 offset:2048
	ds_read_b128 v[178:181], v141 offset:4096
	ds_read_b128 v[182:185], v141 offset:6144
	s_waitcnt lgkmcnt(0)
	s_waitcnt vmcnt(0) lgkmcnt(0)
	s_barrier
	v_mfma_f32_32x32x16_bf16 v[114:129], v[132:135], v[142:145], v[114:129]
	v_mfma_f32_32x32x16_bf16 v[98:113], v[136:139], v[142:145], v[98:113]
	v_and_b32_e32 v143, 64, v130
	v_and_b32_e32 v144, 31, v130
	v_mfma_f32_32x32x16_bf16 v[82:97], v[132:135], v[146:149], v[82:97]
	v_mfma_f32_32x32x16_bf16 v[66:81], v[136:139], v[146:149], v[66:81]
	v_mfma_f32_32x32x16_bf16 v[50:65], v[132:135], v[150:153], v[50:65]
	v_mfma_f32_32x32x16_bf16 v[34:49], v[136:139], v[150:153], v[34:49]
	v_mfma_f32_32x32x16_bf16 v[18:33], v[132:135], v[154:157], v[18:33]
	v_mfma_f32_32x32x16_bf16 v[2:17], v[136:139], v[154:157], v[2:17]
	v_mfma_f32_32x32x16_bf16 v[114:129], v[158:161], v[170:173], v[114:129]
	v_mfma_f32_32x32x16_bf16 v[98:113], v[162:165], v[170:173], v[98:113]
	v_mfma_f32_32x32x16_bf16 v[82:97], v[158:161], v[174:177], v[82:97]
	v_mfma_f32_32x32x16_bf16 v[66:81], v[162:165], v[174:177], v[66:81]
	v_mfma_f32_32x32x16_bf16 v[50:65], v[158:161], v[178:181], v[50:65]
	v_mfma_f32_32x32x16_bf16 v[34:49], v[162:165], v[178:181], v[34:49]
	v_mfma_f32_32x32x16_bf16 v[18:33], v[158:161], v[182:185], v[18:33]
	v_mfma_f32_32x32x16_bf16 v[2:17], v[162:165], v[182:185], v[2:17]
	s_and_saveexec_b64 s[12:13], s[48:49]
	s_cbranch_execz .LBB0_1558
	v_mul_u32_u24_e32 v0, 0x210, v144
	v_lshlrev_b32_e32 v131, 4, v140
	v_lshlrev_b32_e32 v132, 2, v143
	v_add3_u32 v0, v0, v131, v132
	ds_write_b128 v0, v[114:117]
	ds_write_b128 v0, v[118:121] offset:32
	ds_write_b128 v0, v[122:125] offset:64
	ds_write_b128 v0, v[126:129] offset:96
	ds_write_b128 v0, v[98:101] offset:128
	ds_write_b128 v0, v[102:105] offset:160
	ds_write_b128 v0, v[106:109] offset:192
	ds_write_b128 v0, v[110:113] offset:224
	ds_write_b128 v0, v[82:85] offset:16896
	ds_write_b128 v0, v[86:89] offset:16928
	ds_write_b128 v0, v[90:93] offset:16960
	ds_write_b128 v0, v[94:97] offset:16992
	ds_write_b128 v0, v[66:69] offset:17024
	ds_write_b128 v0, v[70:73] offset:17056
	ds_write_b128 v0, v[74:77] offset:17088
	ds_write_b128 v0, v[78:81] offset:17120
	ds_write_b128 v0, v[50:53] offset:33792
	ds_write_b128 v0, v[54:57] offset:33824
	ds_write_b128 v0, v[58:61] offset:33856
	ds_write_b128 v0, v[62:65] offset:33888
	ds_write_b128 v0, v[34:37] offset:33920
	ds_write_b128 v0, v[38:41] offset:33952
	ds_write_b128 v0, v[42:45] offset:33984
	ds_write_b128 v0, v[46:49] offset:34016
	v_or_b32_e32 v0, 0x60, v130
	v_mul_lo_u32 v0, v0, s94
	v_add3_u32 v0, v0, v131, v132
	ds_write_b128 v0, v[18:21]
	ds_write_b128 v0, v[22:25] offset:32
	ds_write_b128 v0, v[26:29] offset:64
	ds_write_b128 v0, v[30:33] offset:96
	ds_write_b128 v0, v[2:5] offset:128
	ds_write_b128 v0, v[6:9] offset:160
	ds_write_b128 v0, v[10:13] offset:192
	ds_write_b128 v0, v[14:17] offset:224

.LBB0_1654:
	s_mul_i32 s22, s19, 0x6000
	v_add_u32_e32 v146, s22, v144
	v_add_u32_e32 v147, s22, v142
	v_add_u32_e32 v198, v146, v141
	v_add_u32_e32 v199, v147, v141
	v_add_u32_e32 v200, v146, v140
	v_add_u32_e32 v201, v147, v140
	s_waitcnt vmcnt(6)
	s_barrier
	ds_read_b128 v[146:149], v198
	ds_read_b128 v[150:153], v198 offset:2048
	ds_read_b128 v[154:157], v199
	ds_read_b128 v[158:161], v199 offset:2048
	ds_read_b128 v[162:165], v199 offset:4096
	ds_read_b128 v[170:173], v199 offset:6144
	ds_read_b128 v[174:177], v200
	ds_read_b128 v[178:181], v200 offset:2048
	ds_read_b128 v[182:185], v201
	ds_read_b128 v[186:189], v201 offset:2048
	ds_read_b128 v[190:193], v201 offset:4096
	ds_read_b128 v[194:197], v201 offset:6144
	s_waitcnt lgkmcnt(0)
	v_mfma_f32_32x32x16_bf16 v[114:129], v[146:149], v[154:157], v[114:129]
	v_mfma_f32_32x32x16_bf16 v[82:97], v[146:149], v[158:161], v[82:97]
	v_mfma_f32_32x32x16_bf16 v[50:65], v[146:149], v[162:165], v[50:65]
	v_mfma_f32_32x32x16_bf16 v[18:33], v[146:149], v[170:173], v[18:33]
	s_add_i32 s20, s22, 0xffffa000
	s_cmp_gt_i32 s19, 0
	s_cselect_b32 s20, s20, 0xc000
	v_add_u32_e32 v148, s20, v145
	v_lshl_add_u64 v[136:137], v[132:133], 0, v[0:1]
	v_readfirstlane_b32 s20, v148
	v_add_u32_e32 v146, 0x1000, v148
	v_lshl_add_u64 v[134:135], v[136:137], 0, s[34:35]
	s_mov_b32 m0, s20
	v_readfirstlane_b32 s20, v146
	v_add_u32_e32 v146, 0x2000, v148
	global_load_lds_dwordx4 v[134:135], off
	v_mfma_f32_32x32x16_bf16 v[98:113], v[150:153], v[154:157], v[98:113]
	v_lshl_add_u64 v[134:135], v[136:137], 0, s[36:37]
	s_mov_b32 m0, s20
	v_readfirstlane_b32 s20, v146
	v_add_u32_e32 v146, 0x3000, v148
	global_load_lds_dwordx4 v[134:135], off
	v_mfma_f32_32x32x16_bf16 v[66:81], v[150:153], v[158:161], v[66:81]
	v_lshl_add_u64 v[134:135], v[136:137], 0, s[38:39]
	s_mov_b32 m0, s20
	v_readfirstlane_b32 s20, v146
	global_load_lds_dwordx4 v[134:135], off
	v_mfma_f32_32x32x16_bf16 v[34:49], v[150:153], v[162:165], v[34:49]
	v_lshl_add_u64 v[134:135], v[136:137], 0, s[40:41]
	s_mov_b32 m0, s20
	s_mov_b64 s[20:21], 0x1180000
	global_load_lds_dwordx4 v[134:135], off
	v_mfma_f32_32x32x16_bf16 v[2:17], v[150:153], v[170:173], v[2:17]
	v_lshl_add_u64 v[134:135], v[130:131], 0, v[0:1]
	v_add_u32_e32 v149, 0x4000, v148
	v_lshl_add_u64 v[146:147], v[134:135], 0, s[20:21]
	v_readfirstlane_b32 s20, v149
	s_mov_b32 m0, s20
	s_mov_b64 s[20:21], 0x1181000
	v_add_u32_e32 v148, 0x5000, v148
	global_load_lds_dwordx4 v[146:147], off
	v_mfma_f32_32x32x16_bf16 v[114:129], v[174:177], v[182:185], v[114:129]
	v_lshl_add_u64 v[146:147], v[134:135], 0, s[20:21]
	v_readfirstlane_b32 s20, v148
	s_mov_b32 m0, s20
	s_add_i32 s20, s19, 1
	s_cmp_lg_u32 s19, 2
	s_cselect_b32 s19, s20, 0
	s_mul_i32 s20, s19, 0x6000
	s_add_i32 s21, s20, 0xffffa000
	global_load_lds_dwordx4 v[146:147], off
	v_mfma_f32_32x32x16_bf16 v[98:113], v[178:181], v[182:185], v[98:113]
	s_waitcnt vmcnt(6)
	s_barrier
	s_cmp_gt_i32 s19, 0
	s_cselect_b32 s21, s21, 0xc000
	s_mov_b64 s[22:23], 0x11c0000
	v_lshl_add_u64 v[132:133], v[132:133], 0, s[96:97]
	v_add_u32_e32 v148, s21, v145
	v_add_u32_e32 v149, 0x1000, v148
	v_readfirstlane_b32 s21, v148
	v_lshl_add_u64 v[146:147], v[136:137], 0, s[88:89]
	s_mov_b32 m0, s21
	v_readfirstlane_b32 s21, v149
	v_add_u32_e32 v149, 0x2000, v148
	global_load_lds_dwordx4 v[146:147], off
	v_mfma_f32_32x32x16_bf16 v[82:97], v[174:177], v[186:189], v[82:97]
	v_lshl_add_u64 v[146:147], v[136:137], 0, s[4:5]
	s_mov_b32 m0, s21
	v_readfirstlane_b32 s21, v149
	global_load_lds_dwordx4 v[146:147], off
	v_mfma_f32_32x32x16_bf16 v[66:81], v[178:181], v[186:189], v[66:81]
	v_lshl_add_u64 v[146:147], v[136:137], 0, s[84:85]
	s_mov_b32 m0, s21
	v_lshl_add_u64 v[136:137], v[136:137], 0, s[86:87]
	global_load_lds_dwordx4 v[146:147], off
	v_mfma_f32_32x32x16_bf16 v[50:65], v[174:177], v[190:193], v[50:65]
	v_add_u32_e32 v146, 0x3000, v148
	s_nop 0
	v_readfirstlane_b32 s21, v146
	v_add_u32_e32 v146, 0x4000, v148
	s_mov_b32 m0, s21
	v_readfirstlane_b32 s21, v146
	global_load_lds_dwordx4 v[136:137], off
	v_mfma_f32_32x32x16_bf16 v[34:49], v[178:181], v[190:193], v[34:49]
	v_lshl_add_u64 v[136:137], v[134:135], 0, s[22:23]
	s_mov_b32 m0, s21
	s_mov_b64 s[22:23], 0x11c1000
	global_load_lds_dwordx4 v[136:137], off
	v_mfma_f32_32x32x16_bf16 v[18:33], v[174:177], v[194:197], v[18:33]
	v_add_u32_e32 v136, 0x5000, v148
	v_lshl_add_u64 v[134:135], v[134:135], 0, s[22:23]
	v_readfirstlane_b32 s21, v136
	s_mov_b32 m0, s21
	s_nop 0
	global_load_lds_dwordx4 v[134:135], off
	v_mfma_f32_32x32x16_bf16 v[2:17], v[178:181], v[194:197], v[2:17]
	v_add_u32_e32 v134, s20, v144
	v_add_u32_e32 v135, s20, v142
	s_add_i32 s20, s19, 1
	s_cmp_lg_u32 s19, 2
	s_cselect_b32 s19, s20, 0
	s_add_i32 s18, s18, -2
	s_mov_b64 s[20:21], 0x80000
	v_lshl_add_u64 v[130:131], v[130:131], 0, s[20:21]
	s_cmp_eq_u32 s18, 0
	v_add_u32_e32 v194, v134, v141
	v_add_u32_e32 v195, v135, v141
	v_add_u32_e32 v196, v134, v140
	v_add_u32_e32 v197, v135, v140
	ds_read_b128 v[134:137], v194
	ds_read_b128 v[146:149], v194 offset:2048
	ds_read_b128 v[150:153], v195
	ds_read_b128 v[154:157], v195 offset:2048
	ds_read_b128 v[158:161], v195 offset:4096
	ds_read_b128 v[162:165], v195 offset:6144
	ds_read_b128 v[170:173], v196
	ds_read_b128 v[174:177], v196 offset:2048
	ds_read_b128 v[178:181], v197
	ds_read_b128 v[182:185], v197 offset:2048
	ds_read_b128 v[186:189], v197 offset:4096
	ds_read_b128 v[190:193], v197 offset:6144
	s_waitcnt lgkmcnt(0)
	s_nop 0
	v_mfma_f32_32x32x16_bf16 v[114:129], v[134:137], v[150:153], v[114:129]
	v_mfma_f32_32x32x16_bf16 v[98:113], v[146:149], v[150:153], v[98:113]
	v_mfma_f32_32x32x16_bf16 v[82:97], v[134:137], v[154:157], v[82:97]
	v_mfma_f32_32x32x16_bf16 v[66:81], v[146:149], v[154:157], v[66:81]
	v_mfma_f32_32x32x16_bf16 v[50:65], v[134:137], v[158:161], v[50:65]
	v_mfma_f32_32x32x16_bf16 v[34:49], v[146:149], v[158:161], v[34:49]
	v_mfma_f32_32x32x16_bf16 v[18:33], v[134:137], v[162:165], v[18:33]
	v_mfma_f32_32x32x16_bf16 v[2:17], v[146:149], v[162:165], v[2:17]
	v_mfma_f32_32x32x16_bf16 v[114:129], v[170:173], v[178:181], v[114:129]
	v_mfma_f32_32x32x16_bf16 v[98:113], v[174:177], v[178:181], v[98:113]
	v_mfma_f32_32x32x16_bf16 v[82:97], v[170:173], v[182:185], v[82:97]
	v_mfma_f32_32x32x16_bf16 v[66:81], v[174:177], v[182:185], v[66:81]
	v_mfma_f32_32x32x16_bf16 v[50:65], v[170:173], v[186:189], v[50:65]
	v_mfma_f32_32x32x16_bf16 v[34:49], v[174:177], v[186:189], v[34:49]
	v_mfma_f32_32x32x16_bf16 v[18:33], v[170:173], v[190:193], v[18:33]
	v_mfma_f32_32x32x16_bf16 v[2:17], v[174:177], v[190:193], v[2:17]
	s_cbranch_scc0 .LBB0_1654
	s_waitcnt vmcnt(6)
	s_barrier
	v_add_u32_e32 v0, v144, v141
	v_add_u32_e32 v164, v142, v141
	v_add_u32_e32 v165, v144, v140
	v_add_u32_e32 v190, v142, v140
	ds_read_b128 v[130:133], v0
	ds_read_b128 v[134:137], v0 offset:2048
	ds_read_b128 v[144:147], v164
	ds_read_b128 v[148:151], v164 offset:2048
	ds_read_b128 v[152:155], v164 offset:4096
	ds_read_b128 v[156:159], v164 offset:6144
	ds_read_b128 v[160:163], v165
	ds_read_b128 v[170:173], v165 offset:2048
	ds_read_b128 v[174:177], v190
	ds_read_b128 v[178:181], v190 offset:2048
	ds_read_b128 v[182:185], v190 offset:4096
	ds_read_b128 v[186:189], v190 offset:6144
	s_waitcnt lgkmcnt(0)
	v_or_b32_e32 v0, 0xa000, v143
	v_mfma_f32_32x32x16_bf16 v[34:49], v[134:137], v[152:155], v[34:49]
	s_waitcnt vmcnt(0)
	s_barrier
	v_add_u32_e32 v164, v141, v0
	v_add_u32_e32 v0, v140, v0
	v_mfma_f32_32x32x16_bf16 v[50:65], v[130:133], v[152:155], v[50:65]
	v_mfma_f32_32x32x16_bf16 v[114:129], v[130:133], v[144:147], v[114:129]
	v_mfma_f32_32x32x16_bf16 v[98:113], v[134:137], v[144:147], v[98:113]
	v_mfma_f32_32x32x16_bf16 v[82:97], v[130:133], v[148:151], v[82:97]
	v_mfma_f32_32x32x16_bf16 v[66:81], v[134:137], v[148:151], v[66:81]
	v_mfma_f32_32x32x16_bf16 v[18:33], v[130:133], v[156:159], v[18:33]
	v_add_u32_e32 v130, 0x6000, v142
	v_add_u32_e32 v165, v141, v130
	v_mfma_f32_32x32x16_bf16 v[2:17], v[134:137], v[156:159], v[2:17]
	v_mfma_f32_32x32x16_bf16 v[34:49], v[170:173], v[182:185], v[34:49]
	v_mfma_f32_32x32x16_bf16 v[50:65], v[160:163], v[182:185], v[50:65]
	v_mfma_f32_32x32x16_bf16 v[114:129], v[160:163], v[174:177], v[114:129]
	v_mfma_f32_32x32x16_bf16 v[98:113], v[170:173], v[174:177], v[98:113]
	v_mfma_f32_32x32x16_bf16 v[82:97], v[160:163], v[178:181], v[82:97]
	v_mfma_f32_32x32x16_bf16 v[66:81], v[170:173], v[178:181], v[66:81]
	v_mfma_f32_32x32x16_bf16 v[18:33], v[160:163], v[186:189], v[18:33]
	v_mfma_f32_32x32x16_bf16 v[2:17], v[170:173], v[186:189], v[2:17]
	v_add_u32_e32 v186, v140, v130
	ds_read_b128 v[130:133], v164
	ds_read_b128 v[134:137], v164 offset:2048
	ds_read_b128 v[140:143], v165
	ds_read_b128 v[144:147], v165 offset:2048
	ds_read_b128 v[148:151], v165 offset:4096
	ds_read_b128 v[152:155], v165 offset:6144
	ds_read_b128 v[156:159], v0
	ds_read_b128 v[160:163], v0 offset:2048
	ds_read_b128 v[170:173], v186
	ds_read_b128 v[174:177], v186 offset:2048
	ds_read_b128 v[178:181], v186 offset:4096
	ds_read_b128 v[182:185], v186 offset:6144
	s_waitcnt lgkmcnt(0)
	v_lshlrev_b32_e32 v0, 1, v138
	v_and_b32_e32 v0, 0x80, v0
	v_lshl_or_b32 v0, v139, 3, v0
	s_waitcnt vmcnt(0) lgkmcnt(0)
	s_barrier
	v_mfma_f32_32x32x16_bf16 v[34:49], v[134:137], v[148:151], v[34:49]
	v_mfma_f32_32x32x16_bf16 v[50:65], v[130:133], v[148:151], v[50:65]
	v_mfma_f32_32x32x16_bf16 v[34:49], v[160:163], v[178:181], v[34:49]
	v_mfma_f32_32x32x16_bf16 v[50:65], v[156:159], v[178:181], v[50:65]
	s_nop 10
	v_max_f32_e32 v34, v34, v34
	v_max_f32_e32 v35, v35, v35
	v_max_f32_e32 v36, v36, v36
	v_max_f32_e32 v37, v37, v37
	v_max_f32_e32 v34, 0, v34
	v_max_f32_e32 v35, 0, v35
	v_max_f32_e32 v36, 0, v36
	v_mfma_f32_32x32x16_bf16 v[18:33], v[130:133], v[152:155], v[18:33]
	v_max_f32_e32 v37, 0, v37
	v_mul_f32_e64 v34, v34, v34
	v_mul_f32_e64 v35, v35, v35
	v_mul_f32_e64 v36, v36, v36
	v_mul_f32_e64 v37, v37, v37
	v_max_f32_e32 v50, v50, v50
	v_max_f32_e32 v51, v51, v51
	v_max_f32_e32 v52, v52, v52
	v_max_f32_e32 v53, v53, v53
	v_cvt_pk_bf16_f32 v34, v34, v35
	v_cvt_pk_bf16_f32 v35, v36, v37
	v_max_f32_e32 v36, v38, v38
	v_max_f32_e32 v37, v39, v39
	v_max_f32_e32 v38, v40, v40
	v_max_f32_e32 v39, v41, v41
	v_mfma_f32_32x32x16_bf16 v[114:129], v[130:133], v[140:143], v[114:129]
	v_max_f32_e32 v50, 0, v50
	v_max_f32_e32 v51, 0, v51
	v_max_f32_e32 v52, 0, v52
	v_max_f32_e32 v53, 0, v53
	v_max_f32_e32 v36, 0, v36
	v_max_f32_e32 v37, 0, v37
	v_max_f32_e32 v38, 0, v38
	v_mfma_f32_32x32x16_bf16 v[82:97], v[130:133], v[144:147], v[82:97]
	v_and_b32_e32 v130, 0xfffff9f, v138
	v_max_f32_e32 v39, 0, v39
	v_mad_u64_u32 v[130:131], s[18:19], v130, s3, v[0:1]
	v_mul_f32_e64 v50, v50, v50
	v_mul_f32_e64 v51, v51, v51
	v_pk_mul_f32 v[52:53], v[52:53], v[52:53]
	v_pk_mul_f32 v[36:37], v[36:37], v[36:37]
	v_pk_mul_f32 v[38:39], v[38:39], v[38:39]
	v_cvt_pk_bf16_f32 v50, v50, v51
	v_cvt_pk_bf16_f32 v51, v52, v53
	v_max_f32_e32 v52, v54, v54
	v_max_f32_e32 v54, v56, v56
	v_add_u32_e32 v56, 0x4000, v130
	v_cvt_pk_bf16_f32 v36, v36, v37
	v_cvt_pk_bf16_f32 v37, v38, v39
	v_mfma_f32_32x32x16_bf16 v[18:33], v[156:159], v[182:185], v[18:33]
	ds_write2_b64 v56, v[34:35], v[36:37] offset0:136 offset1:138
	v_max_f32_e32 v34, v42, v42
	v_max_f32_e32 v35, v43, v43
	v_max_f32_e32 v36, v44, v44
	v_max_f32_e32 v37, v45, v45
	v_max_f32_e32 v34, 0, v34
	v_max_f32_e32 v35, 0, v35
	v_max_f32_e32 v36, 0, v36
	v_max_f32_e32 v37, 0, v37
	v_pk_mul_f32 v[34:35], v[34:35], v[34:35]
	v_pk_mul_f32 v[36:37], v[36:37], v[36:37]
	v_cvt_pk_bf16_f32 v34, v34, v35
	v_cvt_pk_bf16_f32 v35, v36, v37
	v_max_f32_e32 v36, v46, v46
	v_max_f32_e32 v37, v47, v47
	v_max_f32_e32 v38, v48, v48
	v_max_f32_e32 v39, v49, v49
	v_max_f32_e32 v36, 0, v36
	v_max_f32_e32 v37, 0, v37
	v_max_f32_e32 v38, 0, v38
	v_max_f32_e32 v39, 0, v39
	v_mfma_f32_32x32x16_bf16 v[82:97], v[156:159], v[174:177], v[82:97]
	v_mul_f32_e64 v36, v36, v36
	v_mul_f32_e64 v37, v37, v37
	v_mul_f32_e64 v38, v38, v38
	v_mul_f32_e64 v39, v39, v39
	v_cvt_pk_bf16_f32 v36, v36, v37
	v_cvt_pk_bf16_f32 v37, v38, v39
	ds_write2_b64 v56, v[34:35], v[36:37] offset0:140 offset1:142
	v_or_b32_e32 v34, 0x60, v138
	v_mad_u64_u32 v[34:35], s[18:19], v34, s3, v[0:1]
	v_max_f32_e32 v0, v18, v18
	v_max_f32_e32 v18, 0, v0
	v_max_f32_e32 v0, v19, v19
	v_max_f32_e32 v19, 0, v0
	v_max_f32_e32 v0, v20, v20
	v_max_f32_e32 v20, 0, v0
	v_max_f32_e32 v0, v21, v21
	v_mfma_f32_32x32x16_bf16 v[2:17], v[134:137], v[152:155], v[2:17]
	v_max_f32_e32 v21, 0, v0
	v_max_f32_e32 v82, v82, v82
	v_max_f32_e32 v83, v83, v83
	v_max_f32_e32 v84, v84, v84
	v_max_f32_e32 v85, v85, v85
	v_pk_mul_f32 v[18:19], v[18:19], v[18:19]
	v_pk_mul_f32 v[20:21], v[20:21], v[20:21]
	v_max_f32_e32 v0, v22, v22
	v_max_f32_e32 v82, 0, v82
	v_max_f32_e32 v83, 0, v83
	v_max_f32_e32 v84, 0, v84
	v_max_f32_e32 v85, 0, v85
	v_cvt_pk_bf16_f32 v18, v18, v19
	v_cvt_pk_bf16_f32 v19, v20, v21
	v_max_f32_e32 v20, 0, v0
	v_max_f32_e32 v0, v23, v23
	v_pk_mul_f32 v[82:83], v[82:83], v[82:83]
	v_pk_mul_f32 v[84:85], v[84:85], v[84:85]
	v_max_f32_e32 v21, 0, v0
	v_max_f32_e32 v0, v24, v24
	v_cvt_pk_bf16_f32 v82, v82, v83
	v_cvt_pk_bf16_f32 v83, v84, v85
	v_max_f32_e32 v84, v86, v86
	v_max_f32_e32 v85, v87, v87
	v_max_f32_e32 v86, v88, v88
	v_max_f32_e32 v87, v89, v89
	v_max_f32_e32 v53, v55, v55
	v_max_f32_e32 v55, v57, v57
	v_max_f32_e32 v22, 0, v0
	v_max_f32_e32 v0, v25, v25
	v_mfma_f32_32x32x16_bf16 v[66:81], v[134:137], v[144:147], v[66:81]
	v_max_f32_e32 v84, 0, v84
	v_max_f32_e32 v85, 0, v85
	v_max_f32_e32 v86, 0, v86
	v_max_f32_e32 v87, 0, v87
	v_max_f32_e32 v52, 0, v52
	v_max_f32_e32 v53, 0, v53
	v_max_f32_e32 v54, 0, v54
	v_max_f32_e32 v55, 0, v55
	v_max_f32_e32 v23, 0, v0
	v_pk_mul_f32 v[84:85], v[84:85], v[84:85]
	v_pk_mul_f32 v[86:87], v[86:87], v[86:87]
	v_pk_mul_f32 v[52:53], v[52:53], v[52:53]
	v_pk_mul_f32 v[54:55], v[54:55], v[54:55]
	v_pk_mul_f32 v[20:21], v[20:21], v[20:21]
	v_pk_mul_f32 v[22:23], v[22:23], v[22:23]
	v_cvt_pk_bf16_f32 v84, v84, v85
	v_cvt_pk_bf16_f32 v85, v86, v87
	v_add_u32_e32 v88, 0x2000, v130
	v_cvt_pk_bf16_f32 v52, v52, v53
	v_cvt_pk_bf16_f32 v53, v54, v55
	v_cvt_pk_bf16_f32 v20, v20, v21
	v_cvt_pk_bf16_f32 v21, v22, v23
	v_max_f32_e32 v0, v26, v26
	v_mfma_f32_32x32x16_bf16 v[2:17], v[160:163], v[182:185], v[2:17]
	ds_write2_b64 v88, v[82:83], v[84:85] offset0:64 offset1:66
	ds_write2_b64 v56, v[50:51], v[52:53] offset0:128 offset1:130
	ds_write2_b64 v34, v[18:19], v[20:21] offset1:2
	v_max_f32_e32 v18, 0, v0
	v_max_f32_e32 v0, v27, v27
	v_max_f32_e32 v19, 0, v0
	v_max_f32_e32 v0, v28, v28
	v_max_f32_e32 v20, 0, v0
	v_max_f32_e32 v0, v29, v29
	v_max_f32_e32 v21, 0, v0
	v_mfma_f32_32x32x16_bf16 v[98:113], v[134:137], v[140:143], v[98:113]
	v_mul_f32_e64 v18, v18, v18
	v_mul_f32_e64 v19, v19, v19
	v_mul_f32_e64 v20, v20, v20
	v_mul_f32_e64 v21, v21, v21
	v_max_f32_e32 v0, v30, v30
	v_cvt_pk_bf16_f32 v18, v18, v19
	v_cvt_pk_bf16_f32 v19, v20, v21
	v_max_f32_e32 v20, 0, v0
	v_max_f32_e32 v0, v31, v31
	v_mfma_f32_32x32x16_bf16 v[66:81], v[160:163], v[174:177], v[66:81]
	v_max_f32_e32 v21, 0, v0
	v_max_f32_e32 v0, v32, v32
	v_max_f32_e32 v22, 0, v0
	v_max_f32_e32 v0, v33, v33
	v_max_f32_e32 v23, 0, v0
	v_max_f32_e32 v0, v2, v2
	v_max_f32_e32 v2, 0, v0
	v_max_f32_e32 v0, v3, v3
	v_max_f32_e32 v3, 0, v0
	v_max_f32_e32 v0, v4, v4
	v_max_f32_e32 v4, 0, v0
	v_max_f32_e32 v0, v5, v5
	v_mfma_f32_32x32x16_bf16 v[114:129], v[156:159], v[170:173], v[114:129]
	v_max_f32_e32 v5, 0, v0
	v_max_f32_e32 v66, v66, v66
	v_max_f32_e32 v67, v67, v67
	v_max_f32_e32 v68, v68, v68
	v_max_f32_e32 v69, v69, v69
	v_pk_mul_f32 v[2:3], v[2:3], v[2:3]
	v_pk_mul_f32 v[4:5], v[4:5], v[4:5]
	v_mfma_f32_32x32x16_bf16 v[98:113], v[160:163], v[170:173], v[98:113]
	v_max_f32_e32 v0, v6, v6
	v_max_f32_e32 v66, 0, v66
	v_max_f32_e32 v67, 0, v67
	v_max_f32_e32 v68, 0, v68
	v_max_f32_e32 v69, 0, v69
	v_cvt_pk_bf16_f32 v2, v2, v3
	v_cvt_pk_bf16_f32 v3, v4, v5
	v_max_f32_e32 v4, 0, v0
	v_max_f32_e32 v0, v7, v7
	v_pk_mul_f32 v[66:67], v[66:67], v[66:67]
	v_pk_mul_f32 v[68:69], v[68:69], v[68:69]
	v_max_f32_e32 v5, 0, v0
	v_max_f32_e32 v0, v8, v8
	v_cvt_pk_bf16_f32 v66, v66, v67
	v_cvt_pk_bf16_f32 v67, v68, v69
	v_max_f32_e32 v68, v70, v70
	v_max_f32_e32 v69, v71, v71
	v_max_f32_e32 v70, v72, v72
	v_max_f32_e32 v71, v73, v73
	v_max_f32_e32 v6, 0, v0
	v_max_f32_e32 v0, v9, v9
	v_max_f32_e32 v68, 0, v68
	v_max_f32_e32 v69, 0, v69
	v_max_f32_e32 v70, 0, v70
	v_max_f32_e32 v71, 0, v71
	v_max_f32_e32 v7, 0, v0
	v_pk_mul_f32 v[68:69], v[68:69], v[68:69]
	v_pk_mul_f32 v[70:71], v[70:71], v[70:71]
	v_pk_mul_f32 v[4:5], v[4:5], v[4:5]
	v_pk_mul_f32 v[6:7], v[6:7], v[6:7]
	v_cvt_pk_bf16_f32 v68, v68, v69
	v_cvt_pk_bf16_f32 v69, v70, v71
	v_cvt_pk_bf16_f32 v4, v4, v5
	v_cvt_pk_bf16_f32 v5, v6, v7
	v_max_f32_e32 v0, v10, v10
	v_max_f32_e32 v114, v114, v114
	v_max_f32_e32 v115, v115, v115
	v_max_f32_e32 v116, v116, v116
	v_max_f32_e32 v117, v117, v117
	v_max_f32_e32 v98, v98, v98
	v_max_f32_e32 v99, v99, v99
	v_max_f32_e32 v100, v100, v100
	v_max_f32_e32 v101, v101, v101
	ds_write2_b64 v88, v[66:67], v[68:69] offset0:72 offset1:74
	ds_write2_b64 v34, v[2:3], v[4:5] offset0:8 offset1:10
	v_max_f32_e32 v2, 0, v0
	v_max_f32_e32 v0, v11, v11
	v_max_f32_e32 v114, 0, v114
	v_max_f32_e32 v115, 0, v115
	v_max_f32_e32 v116, 0, v116
	v_max_f32_e32 v117, 0, v117
	v_max_f32_e32 v98, 0, v98
	v_max_f32_e32 v99, 0, v99
	v_max_f32_e32 v100, 0, v100
	v_max_f32_e32 v101, 0, v101
	v_max_f32_e32 v3, 0, v0
	v_max_f32_e32 v0, v12, v12
	v_pk_mul_f32 v[114:115], v[114:115], v[114:115]
	v_pk_mul_f32 v[116:117], v[116:117], v[116:117]
	v_pk_mul_f32 v[98:99], v[98:99], v[98:99]
	v_pk_mul_f32 v[100:101], v[100:101], v[100:101]
	v_max_f32_e32 v4, 0, v0
	v_max_f32_e32 v0, v13, v13
	v_cvt_pk_bf16_f32 v114, v114, v115
	v_cvt_pk_bf16_f32 v115, v116, v117
	v_max_f32_e32 v116, v118, v118
	v_max_f32_e32 v117, v119, v119
	v_max_f32_e32 v118, v120, v120
	v_max_f32_e32 v119, v121, v121
	v_cvt_pk_bf16_f32 v98, v98, v99
	v_cvt_pk_bf16_f32 v99, v100, v101
	v_max_f32_e32 v100, v102, v102
	v_max_f32_e32 v101, v103, v103
	v_max_f32_e32 v102, v104, v104
	v_max_f32_e32 v103, v105, v105
	v_max_f32_e32 v5, 0, v0
	v_max_f32_e32 v116, 0, v116
	v_max_f32_e32 v117, 0, v117
	v_max_f32_e32 v118, 0, v118
	v_max_f32_e32 v119, 0, v119
	v_max_f32_e32 v100, 0, v100
	v_max_f32_e32 v101, 0, v101
	v_max_f32_e32 v102, 0, v102
	v_max_f32_e32 v103, 0, v103
	v_max_f32_e32 v66, v74, v74
	v_max_f32_e32 v67, v75, v75
	v_max_f32_e32 v68, v76, v76
	v_max_f32_e32 v69, v77, v77
	v_pk_mul_f32 v[2:3], v[2:3], v[2:3]
	v_pk_mul_f32 v[4:5], v[4:5], v[4:5]
	v_max_f32_e32 v0, v14, v14
	v_pk_mul_f32 v[116:117], v[116:117], v[116:117]
	v_pk_mul_f32 v[118:119], v[118:119], v[118:119]
	v_pk_mul_f32 v[100:101], v[100:101], v[100:101]
	v_pk_mul_f32 v[102:103], v[102:103], v[102:103]
	v_max_f32_e32 v66, 0, v66
	v_max_f32_e32 v67, 0, v67
	v_max_f32_e32 v68, 0, v68
	v_max_f32_e32 v69, 0, v69
	v_cvt_pk_bf16_f32 v2, v2, v3
	v_cvt_pk_bf16_f32 v3, v4, v5
	v_max_f32_e32 v4, 0, v0
	v_max_f32_e32 v0, v15, v15
	v_cvt_pk_bf16_f32 v116, v116, v117
	v_cvt_pk_bf16_f32 v117, v118, v119
	v_cvt_pk_bf16_f32 v100, v100, v101
	v_cvt_pk_bf16_f32 v101, v102, v103
	v_pk_mul_f32 v[66:67], v[66:67], v[66:67]
	v_pk_mul_f32 v[68:69], v[68:69], v[68:69]
	v_max_f32_e32 v5, 0, v0
	v_max_f32_e32 v0, v16, v16
	ds_write2_b64 v130, v[114:115], v[116:117] offset1:2
	v_max_f32_e32 v114, v122, v122
	v_max_f32_e32 v115, v123, v123
	v_max_f32_e32 v116, v124, v124
	v_max_f32_e32 v117, v125, v125
	ds_write2_b64 v130, v[98:99], v[100:101] offset0:8 offset1:10
	v_max_f32_e32 v98, v106, v106
	v_max_f32_e32 v99, v107, v107
	v_max_f32_e32 v100, v108, v108
	v_max_f32_e32 v101, v109, v109
	v_max_f32_e32 v82, v90, v90
	v_max_f32_e32 v83, v91, v91
	v_max_f32_e32 v84, v92, v92
	v_max_f32_e32 v85, v93, v93
	v_cvt_pk_bf16_f32 v66, v66, v67
	v_cvt_pk_bf16_f32 v67, v68, v69
	v_max_f32_e32 v68, v78, v78
	v_max_f32_e32 v69, v79, v79
	v_max_f32_e32 v70, v80, v80
	v_max_f32_e32 v71, v81, v81
	v_max_f32_e32 v50, v58, v58
	v_max_f32_e32 v51, v59, v59
	v_max_f32_e32 v52, v60, v60
	v_max_f32_e32 v53, v61, v61
	v_max_f32_e32 v6, 0, v0
	v_max_f32_e32 v0, v17, v17
	v_max_f32_e32 v114, 0, v114
	v_max_f32_e32 v115, 0, v115
	v_max_f32_e32 v116, 0, v116
	v_max_f32_e32 v117, 0, v117
	v_max_f32_e32 v98, 0, v98
	v_max_f32_e32 v99, 0, v99
	v_max_f32_e32 v100, 0, v100
	v_max_f32_e32 v101, 0, v101
	v_max_f32_e32 v82, 0, v82
	v_max_f32_e32 v83, 0, v83
	v_max_f32_e32 v84, 0, v84
	v_max_f32_e32 v85, 0, v85
	v_max_f32_e32 v68, 0, v68
	v_max_f32_e32 v69, 0, v69
	v_max_f32_e32 v70, 0, v70
	v_max_f32_e32 v71, 0, v71
	v_max_f32_e32 v50, 0, v50
	v_max_f32_e32 v51, 0, v51
	v_max_f32_e32 v52, 0, v52
	v_max_f32_e32 v53, 0, v53
	v_max_f32_e32 v7, 0, v0
	v_pk_mul_f32 v[114:115], v[114:115], v[114:115]
	v_pk_mul_f32 v[116:117], v[116:117], v[116:117]
	v_pk_mul_f32 v[98:99], v[98:99], v[98:99]
	v_pk_mul_f32 v[100:101], v[100:101], v[100:101]
	v_pk_mul_f32 v[82:83], v[82:83], v[82:83]
	v_pk_mul_f32 v[84:85], v[84:85], v[84:85]
	v_pk_mul_f32 v[68:69], v[68:69], v[68:69]
	v_pk_mul_f32 v[70:71], v[70:71], v[70:71]
	v_pk_mul_f32 v[50:51], v[50:51], v[50:51]
	v_pk_mul_f32 v[52:53], v[52:53], v[52:53]
	v_pk_mul_f32 v[4:5], v[4:5], v[4:5]
	v_pk_mul_f32 v[6:7], v[6:7], v[6:7]
	v_cvt_pk_bf16_f32 v114, v114, v115
	v_cvt_pk_bf16_f32 v115, v116, v117
	v_max_f32_e32 v116, v126, v126
	v_max_f32_e32 v117, v127, v127
	v_max_f32_e32 v118, v128, v128
	v_max_f32_e32 v119, v129, v129
	v_cvt_pk_bf16_f32 v98, v98, v99
	v_cvt_pk_bf16_f32 v99, v100, v101
	v_max_f32_e32 v100, v110, v110
	v_max_f32_e32 v101, v111, v111
	v_max_f32_e32 v102, v112, v112
	v_max_f32_e32 v103, v113, v113
	v_cvt_pk_bf16_f32 v82, v82, v83
	v_cvt_pk_bf16_f32 v83, v84, v85
	v_max_f32_e32 v84, v94, v94
	v_max_f32_e32 v85, v95, v95
	v_max_f32_e32 v86, v96, v96
	v_max_f32_e32 v87, v97, v97
	v_cvt_pk_bf16_f32 v68, v68, v69
	v_cvt_pk_bf16_f32 v69, v70, v71
	v_cvt_pk_bf16_f32 v50, v50, v51
	v_cvt_pk_bf16_f32 v51, v52, v53
	v_max_f32_e32 v52, v62, v62
	v_max_f32_e32 v53, v63, v63
	v_max_f32_e32 v54, v64, v64
	v_max_f32_e32 v55, v65, v65
	v_cvt_pk_bf16_f32 v4, v4, v5
	v_cvt_pk_bf16_f32 v5, v6, v7
	v_bfe_u32 v0, v138, 2, 8
	v_max_f32_e32 v116, 0, v116
	v_max_f32_e32 v117, 0, v117
	v_max_f32_e32 v118, 0, v118
	v_max_f32_e32 v119, 0, v119
	v_max_f32_e32 v100, 0, v100
	v_max_f32_e32 v101, 0, v101
	v_max_f32_e32 v102, 0, v102
	v_max_f32_e32 v103, 0, v103
	v_max_f32_e32 v84, 0, v84
	v_max_f32_e32 v85, 0, v85
	v_max_f32_e32 v86, 0, v86
	v_max_f32_e32 v87, 0, v87
	ds_write2_b64 v88, v[66:67], v[68:69] offset0:76 offset1:78
	v_max_f32_e32 v52, 0, v52
	v_max_f32_e32 v53, 0, v53
	v_max_f32_e32 v54, 0, v54
	v_max_f32_e32 v55, 0, v55
	ds_write2_b64 v34, v[2:3], v[4:5] offset0:12 offset1:14
	v_mul_u32_u24_e32 v5, 0x110, v0
	v_or_b32_e32 v0, s16, v0
	v_pk_mul_f32 v[116:117], v[116:117], v[116:117]
	v_pk_mul_f32 v[118:119], v[118:119], v[118:119]
	v_pk_mul_f32 v[100:101], v[100:101], v[100:101]
	v_pk_mul_f32 v[102:103], v[102:103], v[102:103]
	v_pk_mul_f32 v[84:85], v[84:85], v[84:85]
	v_pk_mul_f32 v[86:87], v[86:87], v[86:87]
	v_pk_mul_f32 v[52:53], v[52:53], v[52:53]
	v_pk_mul_f32 v[54:55], v[54:55], v[54:55]
	v_pk_mul_f32 v[20:21], v[20:21], v[20:21]
	v_pk_mul_f32 v[22:23], v[22:23], v[22:23]
	v_lshlrev_b32_e32 v0, 6, v0
	v_cvt_pk_bf16_f32 v116, v116, v117
	v_cvt_pk_bf16_f32 v117, v118, v119
	v_cvt_pk_bf16_f32 v100, v100, v101
	v_cvt_pk_bf16_f32 v101, v102, v103
	v_cvt_pk_bf16_f32 v84, v84, v85
	v_cvt_pk_bf16_f32 v85, v86, v87
	v_cvt_pk_bf16_f32 v52, v52, v53
	v_cvt_pk_bf16_f32 v53, v54, v55
	v_cvt_pk_bf16_f32 v20, v20, v21
	v_cvt_pk_bf16_f32 v21, v22, v23
	v_and_b32_e32 v4, 3, v138
	v_lshl_add_u64 v[2:3], s[92:93], 0, v[0:1]
	s_mov_b32 s18, 0
	ds_write2_b64 v130, v[114:115], v[116:117] offset0:4 offset1:6
	ds_write2_b64 v130, v[98:99], v[100:101] offset0:12 offset1:14
	ds_write2_b64 v88, v[82:83], v[84:85] offset0:68 offset1:70
	ds_write2_b64 v56, v[50:51], v[52:53] offset0:132 offset1:134
	ds_write2_b64 v34, v[18:19], v[20:21] offset0:4 offset1:6
	s_waitcnt lgkmcnt(0)
	s_barrier

.LBB0_1718:
	s_mul_i32 s18, s1, 0x6000
	v_add_u32_e32 v144, s18, v142
	v_add_u32_e32 v145, s18, v141
	v_add_u32_e32 v148, v144, v135
	v_add_u32_e32 v149, v145, v135
	v_add_u32_e32 v151, v144, v140
	v_add_u32_e32 v164, v145, v140
	s_waitcnt vmcnt(6)
	s_barrier
	ds_read_b128 v[144:147], v148
	ds_read_b128 v[152:155], v148 offset:2048
	ds_read_b128 v[156:159], v149
	ds_read_b128 v[160:163], v149 offset:2048
	ds_read_b128 v[170:173], v149 offset:4096
	ds_read_b128 v[174:177], v149 offset:6144
	ds_read_b128 v[178:181], v151
	ds_read_b128 v[182:185], v151 offset:2048
	ds_read_b128 v[186:189], v164
	ds_read_b128 v[190:193], v164 offset:2048
	ds_read_b128 v[194:197], v164 offset:4096
	ds_read_b128 v[198:201], v164 offset:6144
	s_waitcnt lgkmcnt(0)
	v_mfma_f32_32x32x16_bf16 v[114:129], v[144:147], v[156:159], v[114:129]
	v_mfma_f32_32x32x16_bf16 v[82:97], v[144:147], v[160:163], v[82:97]
	v_mfma_f32_32x32x16_bf16 v[50:65], v[144:147], v[170:173], v[50:65]
	v_mfma_f32_32x32x16_bf16 v[18:33], v[144:147], v[174:177], v[18:33]
	s_add_i32 s16, s18, 0xffffa000
	s_cmp_gt_i32 s1, 0
	s_cselect_b32 s16, s16, 0xc000
	v_add_u32_e32 v146, s16, v143
	v_lshl_add_u64 v[136:137], v[132:133], 0, v[0:1]
	s_mov_b64 s[16:17], 0x6500000
	v_lshl_add_u64 v[138:139], v[136:137], 0, s[16:17]
	v_readfirstlane_b32 s16, v146
	s_mov_b32 m0, s16
	s_mov_b64 s[16:17], 0x6501000
	v_add_u32_e32 v144, 0x1000, v146
	global_load_lds_dwordx4 v[138:139], off
	v_mfma_f32_32x32x16_bf16 v[98:113], v[152:155], v[156:159], v[98:113]
	v_lshl_add_u64 v[138:139], v[136:137], 0, s[16:17]
	v_readfirstlane_b32 s16, v144
	s_mov_b32 m0, s16
	s_mov_b64 s[16:17], 0x6502000
	v_add_u32_e32 v144, 0x2000, v146
	global_load_lds_dwordx4 v[138:139], off
	v_mfma_f32_32x32x16_bf16 v[66:81], v[152:155], v[160:163], v[66:81]
	v_lshl_add_u64 v[138:139], v[136:137], 0, s[16:17]
	v_readfirstlane_b32 s16, v144
	s_mov_b32 m0, s16
	s_mov_b64 s[16:17], 0x6503000
	v_add_u32_e32 v144, 0x3000, v146
	global_load_lds_dwordx4 v[138:139], off
	v_mfma_f32_32x32x16_bf16 v[34:49], v[152:155], v[170:173], v[34:49]
	v_lshl_add_u64 v[138:139], v[136:137], 0, s[16:17]
	v_readfirstlane_b32 s16, v144
	s_mov_b32 m0, s16
	s_mov_b64 s[16:17], 0x1920000
	global_load_lds_dwordx4 v[138:139], off
	v_mfma_f32_32x32x16_bf16 v[2:17], v[152:155], v[174:177], v[2:17]
	v_lshl_add_u64 v[138:139], v[130:131], 0, v[0:1]
	v_add_u32_e32 v147, 0x4000, v146
	v_lshl_add_u64 v[144:145], v[138:139], 0, s[16:17]
	v_readfirstlane_b32 s16, v147
	s_mov_b32 m0, s16
	s_mov_b64 s[16:17], 0x1921000
	v_add_u32_e32 v146, 0x5000, v146
	global_load_lds_dwordx4 v[144:145], off
	v_mfma_f32_32x32x16_bf16 v[114:129], v[178:181], v[186:189], v[114:129]
	v_lshl_add_u64 v[144:145], v[138:139], 0, s[16:17]
	v_readfirstlane_b32 s16, v146
	s_mov_b32 m0, s16
	s_add_i32 s16, s1, 1
	s_cmp_lg_u32 s1, 2
	s_cselect_b32 s1, s16, 0
	s_mul_i32 s16, s1, 0x6000
	s_add_i32 s17, s16, 0xffffa000
	global_load_lds_dwordx4 v[144:145], off
	v_mfma_f32_32x32x16_bf16 v[98:113], v[182:185], v[186:189], v[98:113]
	s_waitcnt vmcnt(6)
	s_barrier
	s_cmp_gt_i32 s1, 0
	s_cselect_b32 s17, s17, 0xc000
	s_mov_b64 s[18:19], 0x6700000
	v_lshl_add_u64 v[130:131], v[130:131], 0, s[58:59]
	v_lshl_add_u64 v[132:133], v[132:133], 0, s[96:97]
	v_add_u32_e32 v146, s17, v143
	v_add_u32_e32 v147, 0x1000, v146
	v_readfirstlane_b32 s17, v146
	v_lshl_add_u64 v[144:145], v[136:137], 0, s[18:19]
	s_mov_b32 m0, s17
	s_mov_b64 s[18:19], 0x6701000
	v_readfirstlane_b32 s17, v147
	v_add_u32_e32 v147, 0x2000, v146
	global_load_lds_dwordx4 v[144:145], off
	v_mfma_f32_32x32x16_bf16 v[82:97], v[178:181], v[190:193], v[82:97]
	v_lshl_add_u64 v[144:145], v[136:137], 0, s[18:19]
	s_mov_b32 m0, s17
	s_mov_b64 s[18:19], 0x6702000
	v_readfirstlane_b32 s17, v147
	global_load_lds_dwordx4 v[144:145], off
	v_mfma_f32_32x32x16_bf16 v[66:81], v[182:185], v[190:193], v[66:81]
	v_lshl_add_u64 v[144:145], v[136:137], 0, s[18:19]
	s_mov_b32 m0, s17
	s_mov_b64 s[18:19], 0x6703000
	global_load_lds_dwordx4 v[144:145], off
	v_mfma_f32_32x32x16_bf16 v[50:65], v[178:181], v[194:197], v[50:65]
	v_add_u32_e32 v144, 0x3000, v146
	v_lshl_add_u64 v[136:137], v[136:137], 0, s[18:19]
	v_readfirstlane_b32 s17, v144
	v_add_u32_e32 v144, 0x4000, v146
	s_mov_b32 m0, s17
	s_mov_b64 s[18:19], 0x1930000
	v_readfirstlane_b32 s17, v144
	global_load_lds_dwordx4 v[136:137], off
	v_mfma_f32_32x32x16_bf16 v[34:49], v[182:185], v[194:197], v[34:49]
	v_lshl_add_u64 v[136:137], v[138:139], 0, s[18:19]
	s_mov_b32 m0, s17
	s_mov_b64 s[18:19], 0x1931000
	global_load_lds_dwordx4 v[136:137], off
	v_mfma_f32_32x32x16_bf16 v[18:33], v[178:181], v[198:201], v[18:33]
	v_lshl_add_u64 v[136:137], v[138:139], 0, s[18:19]
	v_add_u32_e32 v138, 0x5000, v146
	s_nop 0
	v_readfirstlane_b32 s17, v138
	s_mov_b32 m0, s17
	s_nop 0
	global_load_lds_dwordx4 v[136:137], off
	v_mfma_f32_32x32x16_bf16 v[2:17], v[182:185], v[198:201], v[2:17]
	v_add_u32_e32 v136, s16, v142
	v_add_u32_e32 v137, s16, v141
	v_add_u32_e32 v148, v136, v135
	v_add_u32_e32 v149, v137, v135
	v_add_u32_e32 v151, v136, v140
	v_add_u32_e32 v164, v137, v140
	s_add_i32 s16, s1, 1
	s_cmp_lg_u32 s1, 2
	s_cselect_b32 s1, s16, 0
	s_add_i32 s0, s0, -2
	s_cmp_eq_u32 s0, 0
	ds_read_b128 v[136:139], v148
	ds_read_b128 v[144:147], v148 offset:2048
	ds_read_b128 v[152:155], v149
	ds_read_b128 v[156:159], v149 offset:2048
	ds_read_b128 v[160:163], v149 offset:4096
	ds_read_b128 v[170:173], v149 offset:6144
	ds_read_b128 v[174:177], v151
	ds_read_b128 v[178:181], v151 offset:2048
	ds_read_b128 v[182:185], v164
	ds_read_b128 v[186:189], v164 offset:2048
	ds_read_b128 v[190:193], v164 offset:4096
	ds_read_b128 v[194:197], v164 offset:6144
	s_waitcnt lgkmcnt(0)
	s_nop 0
	v_mfma_f32_32x32x16_bf16 v[114:129], v[136:139], v[152:155], v[114:129]
	v_mfma_f32_32x32x16_bf16 v[98:113], v[144:147], v[152:155], v[98:113]
	v_mfma_f32_32x32x16_bf16 v[82:97], v[136:139], v[156:159], v[82:97]
	v_mfma_f32_32x32x16_bf16 v[66:81], v[144:147], v[156:159], v[66:81]
	v_mfma_f32_32x32x16_bf16 v[50:65], v[136:139], v[160:163], v[50:65]
	v_mfma_f32_32x32x16_bf16 v[34:49], v[144:147], v[160:163], v[34:49]
	v_mfma_f32_32x32x16_bf16 v[18:33], v[136:139], v[170:173], v[18:33]
	v_mfma_f32_32x32x16_bf16 v[2:17], v[144:147], v[170:173], v[2:17]
	v_mfma_f32_32x32x16_bf16 v[114:129], v[174:177], v[182:185], v[114:129]
	v_mfma_f32_32x32x16_bf16 v[98:113], v[178:181], v[182:185], v[98:113]
	v_mfma_f32_32x32x16_bf16 v[82:97], v[174:177], v[186:189], v[82:97]
	v_mfma_f32_32x32x16_bf16 v[66:81], v[178:181], v[186:189], v[66:81]
	v_mfma_f32_32x32x16_bf16 v[50:65], v[174:177], v[190:193], v[50:65]
	v_mfma_f32_32x32x16_bf16 v[34:49], v[178:181], v[190:193], v[34:49]
	v_mfma_f32_32x32x16_bf16 v[18:33], v[174:177], v[194:197], v[18:33]
	v_mfma_f32_32x32x16_bf16 v[2:17], v[178:181], v[194:197], v[2:17]
	s_cbranch_scc0 .LBB0_1718
	s_mul_i32 s0, s1, 0x6000
	v_add_u32_e32 v0, s0, v142
	v_add_u32_e32 v130, s0, v141
	s_waitcnt vmcnt(6)
	s_barrier
	v_add_u32_e32 v143, v0, v135
	v_add_u32_e32 v148, v130, v135
	v_add_u32_e32 v0, v0, v140
	v_add_u32_e32 v149, v130, v140
	ds_read_b128 v[130:133], v143
	ds_read_b128 v[136:139], v143 offset:2048
	ds_read_b128 v[144:147], v148
	ds_read_b128 v[152:155], v148 offset:2048
	ds_read_b128 v[156:159], v148 offset:4096
	ds_read_b128 v[160:163], v148 offset:6144
	ds_read_b128 v[170:173], v0
	ds_read_b128 v[174:177], v0 offset:2048
	ds_read_b128 v[178:181], v149
	ds_read_b128 v[182:185], v149 offset:2048
	ds_read_b128 v[186:189], v149 offset:4096
	ds_read_b128 v[190:193], v149 offset:6144
	s_waitcnt lgkmcnt(0)
	s_addk_i32 s0, 0x6000
	v_mfma_f32_32x32x16_bf16 v[114:129], v[130:133], v[144:147], v[114:129]
	s_cmp_lg_u32 s1, 2
	s_cselect_b32 s0, s0, 0
	v_add_u32_e32 v0, s0, v142
	s_waitcnt vmcnt(0)
	s_barrier
	v_add_u32_e32 v148, v0, v135
	v_add_u32_e32 v0, v0, v140
	v_mfma_f32_32x32x16_bf16 v[98:113], v[136:139], v[144:147], v[98:113]
	v_mfma_f32_32x32x16_bf16 v[82:97], v[130:133], v[152:155], v[82:97]
	v_mfma_f32_32x32x16_bf16 v[66:81], v[136:139], v[152:155], v[66:81]
	v_mfma_f32_32x32x16_bf16 v[50:65], v[130:133], v[156:159], v[50:65]
	v_mfma_f32_32x32x16_bf16 v[34:49], v[136:139], v[156:159], v[34:49]
	v_mfma_f32_32x32x16_bf16 v[18:33], v[130:133], v[160:163], v[18:33]
	v_add_u32_e32 v130, s0, v141
	v_add_u32_e32 v135, v130, v135
	v_add_u32_e32 v149, v130, v140
	s_movk_i32 s0, 0x80
	v_cmp_gt_u32_e64 s[48:49], s0, v134
	v_mfma_f32_32x32x16_bf16 v[2:17], v[136:139], v[160:163], v[2:17]
	v_mfma_f32_32x32x16_bf16 v[114:129], v[170:173], v[178:181], v[114:129]
	v_mfma_f32_32x32x16_bf16 v[98:113], v[174:177], v[178:181], v[98:113]
	v_mfma_f32_32x32x16_bf16 v[82:97], v[170:173], v[182:185], v[82:97]
	v_mfma_f32_32x32x16_bf16 v[66:81], v[174:177], v[182:185], v[66:81]
	v_mfma_f32_32x32x16_bf16 v[50:65], v[170:173], v[186:189], v[50:65]
	v_mfma_f32_32x32x16_bf16 v[34:49], v[174:177], v[186:189], v[34:49]
	v_mfma_f32_32x32x16_bf16 v[18:33], v[170:173], v[190:193], v[18:33]
	v_mfma_f32_32x32x16_bf16 v[2:17], v[174:177], v[190:193], v[2:17]
	ds_read_b128 v[130:133], v148
	ds_read_b128 v[136:139], v148 offset:2048
	ds_read_b128 v[140:143], v135
	ds_read_b128 v[144:147], v135 offset:2048
	ds_read_b128 v[152:155], v135 offset:4096
	ds_read_b128 v[156:159], v135 offset:6144
	ds_read_b128 v[160:163], v0
	ds_read_b128 v[170:173], v0 offset:2048
	ds_read_b128 v[174:177], v149
	ds_read_b128 v[178:181], v149 offset:2048
	ds_read_b128 v[182:185], v149 offset:4096
	ds_read_b128 v[186:189], v149 offset:6144
	s_waitcnt lgkmcnt(0)
	s_waitcnt vmcnt(0) lgkmcnt(0)
	s_barrier
	v_mfma_f32_32x32x16_bf16 v[114:129], v[130:133], v[140:143], v[114:129]
	v_mfma_f32_32x32x16_bf16 v[98:113], v[136:139], v[140:143], v[98:113]
	v_mfma_f32_32x32x16_bf16 v[82:97], v[130:133], v[144:147], v[82:97]
	v_mfma_f32_32x32x16_bf16 v[66:81], v[136:139], v[144:147], v[66:81]
	v_mfma_f32_32x32x16_bf16 v[50:65], v[130:133], v[152:155], v[50:65]
	v_mfma_f32_32x32x16_bf16 v[34:49], v[136:139], v[152:155], v[34:49]
	v_and_b32_e32 v153, 31, v134
	v_mfma_f32_32x32x16_bf16 v[18:33], v[130:133], v[156:159], v[18:33]
	v_mfma_f32_32x32x16_bf16 v[2:17], v[136:139], v[156:159], v[2:17]
	v_and_b32_e32 v137, 64, v134
	v_mfma_f32_32x32x16_bf16 v[114:129], v[160:163], v[174:177], v[114:129]
	v_mfma_f32_32x32x16_bf16 v[98:113], v[170:173], v[174:177], v[98:113]
	v_mfma_f32_32x32x16_bf16 v[82:97], v[160:163], v[178:181], v[82:97]
	v_mfma_f32_32x32x16_bf16 v[66:81], v[170:173], v[178:181], v[66:81]
	v_mfma_f32_32x32x16_bf16 v[50:65], v[160:163], v[182:185], v[50:65]
	v_mfma_f32_32x32x16_bf16 v[34:49], v[170:173], v[182:185], v[34:49]
	v_mfma_f32_32x32x16_bf16 v[18:33], v[160:163], v[186:189], v[18:33]
	v_mfma_f32_32x32x16_bf16 v[2:17], v[170:173], v[186:189], v[2:17]
	s_and_saveexec_b64 s[0:1], s[48:49]
	s_cbranch_execz .LBB0_1721
	v_mul_u32_u24_e32 v0, 0x210, v153
	v_lshlrev_b32_e32 v130, 4, v150
	v_lshlrev_b32_e32 v131, 2, v137
	v_add3_u32 v0, v0, v130, v131
	ds_write_b128 v0, v[114:117]
	ds_write_b128 v0, v[118:121] offset:32
	ds_write_b128 v0, v[122:125] offset:64
	ds_write_b128 v0, v[126:129] offset:96
	ds_write_b128 v0, v[98:101] offset:128
	ds_write_b128 v0, v[102:105] offset:160
	ds_write_b128 v0, v[106:109] offset:192
	ds_write_b128 v0, v[110:113] offset:224
	ds_write_b128 v0, v[82:85] offset:16896
	ds_write_b128 v0, v[86:89] offset:16928
	ds_write_b128 v0, v[90:93] offset:16960
	ds_write_b128 v0, v[94:97] offset:16992
	ds_write_b128 v0, v[66:69] offset:17024
	ds_write_b128 v0, v[70:73] offset:17056
	ds_write_b128 v0, v[74:77] offset:17088
	ds_write_b128 v0, v[78:81] offset:17120
	ds_write_b128 v0, v[50:53] offset:33792
	ds_write_b128 v0, v[54:57] offset:33824
	ds_write_b128 v0, v[58:61] offset:33856
	ds_write_b128 v0, v[62:65] offset:33888
	ds_write_b128 v0, v[34:37] offset:33920
	ds_write_b128 v0, v[38:41] offset:33952
	ds_write_b128 v0, v[42:45] offset:33984
	ds_write_b128 v0, v[46:49] offset:34016
	v_or_b32_e32 v0, 0x60, v134
	v_mul_lo_u32 v0, v0, s94
	v_add3_u32 v0, v0, v130, v131
	ds_write_b128 v0, v[18:21]
	ds_write_b128 v0, v[22:25] offset:32
	ds_write_b128 v0, v[26:29] offset:64
	ds_write_b128 v0, v[30:33] offset:96
	ds_write_b128 v0, v[2:5] offset:128
	ds_write_b128 v0, v[6:9] offset:160
	ds_write_b128 v0, v[10:13] offset:192
	ds_write_b128 v0, v[14:17] offset:224
